# GATE epilogue: all 32 bf16 x loads issued before the first row (into dead registers) instead of load+wait per row
# baseline (speedup 1.0000x reference)
.LBB0_1494:
	s_ashr_i32 s0, s3, 31
	s_lshr_b32 s0, s0, 24
	s_add_i32 s0, s3, s0
	s_ashr_i32 s1, s0, 8
	s_and_b32 s0, s0, 0xffffff00
	s_sub_i32 s4, s3, s0
	s_ashr_i32 s0, s4, 31
	s_lshr_b32 s0, s0, 29
	s_add_i32 s0, s4, s0
	s_and_b32 s5, s0, -8
	s_lshl_b32 s1, s1, 3
	s_sub_i32 s60, s4, s5
	s_ashr_i32 s46, s0, 3
	s_add_i32 s60, s60, s1
	s_lshl_b32 s61, s46, 6
	s_lshl_b32 s4, s60, 7
	s_lshl_b32 s46, s46, 7
	s_ashr_i32 s5, s4, 31
	s_ashr_i32 s47, s46, 31
	s_lshl_b64 s[4:5], s[4:5], 11
	s_lshl_b64 s[48:49], s[46:47], 8
	s_add_u32 s1, s8, s4
	s_addc_u32 s5, s9, s5
	s_and_b32 s4, s46, 0x700
	s_add_u32 s4, s1, s4
	s_addc_u32 s5, s5, 0
	s_add_u32 s46, s10, s48
	v_readfirstlane_b32 s1, v87
	s_addc_u32 s47, s11, s49
	v_lshl_add_u64 v[0:1], s[4:5], 0, v[64:65]
	s_mov_b32 m0, s1
	v_readfirstlane_b32 s1, v88
	v_lshl_add_u64 v[2:3], s[46:47], 0, v[66:67]
	global_load_lds_dwordx4 v[0:1], off
	s_mov_b32 m0, s1
	v_readfirstlane_b32 s1, v89
	global_load_lds_dwordx4 v[2:3], off
	v_lshl_add_u64 v[4:5], v[0:1], 0, s[18:19]
	s_mov_b32 m0, s1
	v_readfirstlane_b32 s1, v90
	global_load_lds_dwordx4 v[4:5], off
	v_lshl_add_u64 v[4:5], v[2:3], 0, s[20:21]
	s_mov_b32 m0, s1
	v_readfirstlane_b32 s1, v91
	global_load_lds_dwordx4 v[4:5], off
	v_lshl_add_u64 v[4:5], v[0:1], 0, s[22:23]
	s_mov_b32 m0, s1
	v_readfirstlane_b32 s1, v92
	global_load_lds_dwordx4 v[4:5], off
	v_lshl_add_u64 v[4:5], v[2:3], 0, s[24:25]
	s_mov_b32 m0, s1
	v_readfirstlane_b32 s1, v93
	global_load_lds_dwordx4 v[4:5], off
	v_lshl_add_u64 v[4:5], v[0:1], 0, s[26:27]
	s_mov_b32 m0, s1
	v_readfirstlane_b32 s1, v94
	global_load_lds_dwordx4 v[4:5], off
	v_lshl_add_u64 v[4:5], v[2:3], 0, s[28:29]
	s_mov_b32 m0, s1
	v_readfirstlane_b32 s1, v95
	global_load_lds_dwordx4 v[4:5], off
	v_lshl_add_u64 v[4:5], v[0:1], 0, s[30:31]
	s_mov_b32 m0, s1
	v_readfirstlane_b32 s1, v96
	s_waitcnt vmcnt(0)
	s_waitcnt vmcnt(0) lgkmcnt(0)
	s_barrier
	global_load_lds_dwordx4 v[4:5], off
	v_lshl_add_u64 v[4:5], v[2:3], 0, s[30:31]
	s_mov_b32 m0, s1
	v_readfirstlane_b32 s1, v97
	global_load_lds_dwordx4 v[4:5], off
	v_lshl_add_u64 v[4:5], v[0:1], 0, s[34:35]
	s_mov_b32 m0, s1
	v_readfirstlane_b32 s1, v98
	global_load_lds_dwordx4 v[4:5], off
	v_lshl_add_u64 v[4:5], v[2:3], 0, s[36:37]
	s_mov_b32 m0, s1
	v_readfirstlane_b32 s1, v99
	global_load_lds_dwordx4 v[4:5], off
	v_lshl_add_u64 v[4:5], v[0:1], 0, s[38:39]
	s_mov_b32 m0, s1
	v_readfirstlane_b32 s1, v100
	global_load_lds_dwordx4 v[4:5], off
	v_lshl_add_u64 v[4:5], v[2:3], 0, s[40:41]
	s_mov_b32 m0, s1
	v_readfirstlane_b32 s1, v101
	global_load_lds_dwordx4 v[4:5], off
	v_lshl_add_u64 v[0:1], v[0:1], 0, s[42:43]
	s_mov_b32 m0, s1
	v_readfirstlane_b32 s1, v102
	global_load_lds_dwordx4 v[0:1], off
	v_lshl_add_u64 v[0:1], v[2:3], 0, s[44:45]
	s_mov_b32 m0, s1
	s_nop 0
	global_load_lds_dwordx4 v[0:1], off
	ds_read_b128 v[0:3], v103
	ds_read_b128 v[4:7], v104 offset:16384
	ds_read_b128 v[8:11], v104 offset:20480
	ds_read_b128 v[12:15], v104 offset:24576
	ds_read_b128 v[118:121], v104 offset:28672
	ds_read_b128 v[122:125], v105
	ds_read_b128 v[126:129], v106 offset:16384
	ds_read_b128 v[130:133], v106 offset:20480
	ds_read_b128 v[134:137], v106 offset:24576
	ds_read_b128 v[138:141], v106 offset:28672
	s_setprio 1
	s_waitcnt lgkmcnt(0)
	v_mfma_f32_32x32x16_bf16 v[16:31], v[0:3], v[4:7], 0
	v_mfma_f32_32x32x16_bf16 v[32:47], v[0:3], v[8:11], 0
	v_mfma_f32_32x32x16_bf16 v[48:63], v[0:3], v[12:15], 0
	v_mfma_f32_32x32x16_bf16 v[0:15], v[0:3], v[118:121], 0
	s_setprio 0
	ds_read_b128 v[118:121], v107
	ds_read_b128 v[142:145], v108 offset:16384
	ds_read_b128 v[146:149], v108 offset:20480
	ds_read_b128 v[150:153], v108 offset:24576
	ds_read_b128 v[154:157], v108 offset:28672
	s_setprio 1
	v_mfma_f32_32x32x16_bf16 v[16:31], v[122:125], v[126:129], v[16:31]
	v_mfma_f32_32x32x16_bf16 v[32:47], v[122:125], v[130:133], v[32:47]
	v_mfma_f32_32x32x16_bf16 v[48:63], v[122:125], v[134:137], v[48:63]
	v_mfma_f32_32x32x16_bf16 v[0:15], v[122:125], v[138:141], v[0:15]
	s_setprio 0
	ds_read_b128 v[122:125], v109
	ds_read_b128 v[126:129], v110 offset:16384
	ds_read_b128 v[130:133], v110 offset:20480
	ds_read_b128 v[134:137], v110 offset:24576
	ds_read_b128 v[138:141], v110 offset:28672
	s_setprio 1
	s_waitcnt lgkmcnt(0)
	v_mfma_f32_32x32x16_bf16 v[16:31], v[118:121], v[142:145], v[16:31]
	v_mfma_f32_32x32x16_bf16 v[32:47], v[118:121], v[146:149], v[32:47]
	v_mfma_f32_32x32x16_bf16 v[48:63], v[118:121], v[150:153], v[48:63]
	v_mfma_f32_32x32x16_bf16 v[0:15], v[118:121], v[154:157], v[0:15]
	s_setprio 0
	s_setprio 1
	v_mfma_f32_32x32x16_bf16 v[16:31], v[122:125], v[126:129], v[16:31]
	v_mfma_f32_32x32x16_bf16 v[32:47], v[122:125], v[130:133], v[32:47]
	v_mfma_f32_32x32x16_bf16 v[48:63], v[122:125], v[134:137], v[48:63]
	v_mfma_f32_32x32x16_bf16 v[0:15], v[122:125], v[138:141], v[0:15]
	s_setprio 0
	s_waitcnt vmcnt(0)
	s_waitcnt vmcnt(0)
	s_barrier
	ds_read_b128 v[118:121], v103 offset:32768
	ds_read_b128 v[122:125], v104 offset:49152
	ds_read_b128 v[126:129], v104 offset:53248
	ds_read_b128 v[130:133], v104 offset:57344
	ds_read_b128 v[134:137], v104 offset:61440
	ds_read_b128 v[138:141], v105 offset:32768
	ds_read_b128 v[142:145], v106 offset:49152
	ds_read_b128 v[146:149], v106 offset:53248
	ds_read_b128 v[150:153], v106 offset:57344
	ds_read_b128 v[154:157], v106 offset:61440
	s_setprio 1
	s_waitcnt lgkmcnt(8)
	v_mfma_f32_32x32x16_bf16 v[16:31], v[118:121], v[122:125], v[16:31]
	s_waitcnt lgkmcnt(7)
	v_mfma_f32_32x32x16_bf16 v[32:47], v[118:121], v[126:129], v[32:47]
	s_waitcnt lgkmcnt(6)
	v_mfma_f32_32x32x16_bf16 v[48:63], v[118:121], v[130:133], v[48:63]
	s_waitcnt lgkmcnt(5)
	v_mfma_f32_32x32x16_bf16 v[0:15], v[118:121], v[134:137], v[0:15]
	s_setprio 0
	ds_read_b128 v[118:121], v107 offset:32768
	ds_read_b128 v[122:125], v108 offset:49152
	ds_read_b128 v[126:129], v108 offset:53248
	ds_read_b128 v[130:133], v108 offset:57344
	ds_read_b128 v[134:137], v108 offset:61440
	s_setprio 1
	s_waitcnt lgkmcnt(8)
	v_mfma_f32_32x32x16_bf16 v[16:31], v[138:141], v[142:145], v[16:31]
	s_waitcnt lgkmcnt(7)
	v_mfma_f32_32x32x16_bf16 v[32:47], v[138:141], v[146:149], v[32:47]
	s_waitcnt lgkmcnt(6)
	v_mfma_f32_32x32x16_bf16 v[48:63], v[138:141], v[150:153], v[48:63]
	s_waitcnt lgkmcnt(5)
	v_mfma_f32_32x32x16_bf16 v[0:15], v[138:141], v[154:157], v[0:15]
	s_setprio 0
	ds_read_b128 v[138:141], v109 offset:32768
	ds_read_b128 v[142:145], v110 offset:49152
	ds_read_b128 v[146:149], v110 offset:53248
	ds_read_b128 v[150:153], v110 offset:57344
	ds_read_b128 v[154:157], v110 offset:61440
	s_setprio 1
	s_waitcnt lgkmcnt(8)
	v_mfma_f32_32x32x16_bf16 v[16:31], v[118:121], v[122:125], v[16:31]
	s_waitcnt lgkmcnt(7)
	v_mfma_f32_32x32x16_bf16 v[32:47], v[118:121], v[126:129], v[32:47]
	s_waitcnt lgkmcnt(6)
	v_mfma_f32_32x32x16_bf16 v[48:63], v[118:121], v[130:133], v[48:63]
	s_waitcnt lgkmcnt(5)
	v_mfma_f32_32x32x16_bf16 v[0:15], v[118:121], v[134:137], v[0:15]
	s_setprio 0
	s_setprio 1
	s_waitcnt lgkmcnt(3)
	v_mfma_f32_32x32x16_bf16 v[16:31], v[138:141], v[142:145], v[16:31]
	s_waitcnt lgkmcnt(2)
	v_mfma_f32_32x32x16_bf16 v[32:47], v[138:141], v[146:149], v[32:47]
	s_waitcnt lgkmcnt(1)
	v_mfma_f32_32x32x16_bf16 v[48:63], v[138:141], v[150:153], v[48:63]
	s_waitcnt lgkmcnt(0)
	v_mfma_f32_32x32x16_bf16 v[0:15], v[138:141], v[154:157], v[0:15]
	s_setprio 0
	ds_read_b128 v[118:121], v111
	s_ashr_i32 s46, s0, 7
	s_lshl_b32 s0, s46, 11
	s_ashr_i32 s1, s0, 31
	s_lshl_b64 s[0:1], s[0:1], 2
	s_waitcnt lgkmcnt(0)
	v_readfirstlane_b32 s4, v118
	v_readfirstlane_b32 s5, v119
	s_add_u32 s0, s4, s0
	s_addc_u32 s1, s5, s1
	s_lshl_b32 s4, s46, 10
	s_ashr_i32 s5, s4, 31
	v_readfirstlane_b32 s47, v120
	s_lshl_b64 s[4:5], s[4:5], 2
	v_readfirstlane_b32 s48, v121
	s_add_u32 s4, s47, s4
	s_addc_u32 s5, s48, s5
	s_ashr_i32 s47, s46, 31
	s_lshl_b64 s[46:47], s[46:47], 25
	s_add_u32 s48, s50, s46
	s_addc_u32 s49, s51, s47
	s_add_u32 s46, s52, s46
	s_addc_u32 s47, s53, s47
	s_and_b32 s61, s61, 0x3c0
	v_or_b32_e32 v124, s61, v70
	v_lshlrev_b32_e32 v68, 2, v124
	global_load_dword v119, v68, s[4:5]
	global_load_dword v122, v68, s[4:5] offset:128
	global_load_dword v117, v68, s[0:1]
	global_load_dword v118, v68, s[0:1] offset:128
	v_lshl_add_u64 v[120:121], s[0:1], 0, v[68:69]
	v_add_co_u32_e32 v120, vcc, s54, v120
	s_waitcnt vmcnt(3)
	v_mul_f32_e32 v68, 0xbfb8aa3b, v119
	v_exp_f32_e32 v125, v68
	s_waitcnt vmcnt(2)
	v_mul_f32_e32 v119, 0xbfb8aa3b, v122
	v_exp_f32_e32 v128, v119
	v_addc_co_u32_e32 v121, vcc, 0, v121, vcc
	v_add_f32_e32 v126, 1.0, v125
	global_load_dword v119, v[120:121], off
	global_load_dword v68, v[120:121], off offset:128
	v_frexp_mant_f32_e32 v130, v126
	v_cvt_f64_f32_e32 v[120:121], v126
	v_add_f32_e32 v127, 1.0, v128
	v_add_f32_e32 v129, -1.0, v126
	v_frexp_exp_i32_f64_e32 v120, v[120:121]
	v_cmp_gt_f32_e32 vcc, s55, v130
	v_add_f32_e32 v131, -1.0, v127
	v_frexp_mant_f32_e32 v132, v127
	v_cvt_f64_f32_e32 v[122:123], v127
	v_sub_f32_e32 v133, v129, v126
	v_subbrev_co_u32_e32 v120, vcc, 0, v120, vcc
	v_sub_f32_e32 v129, v125, v129
	v_sub_f32_e32 v121, v131, v127
	v_frexp_exp_i32_f64_e32 v122, v[122:123]
	v_add_f32_e32 v123, 1.0, v133
	v_cmp_gt_f32_e32 vcc, s55, v132
	v_sub_f32_e32 v131, v128, v131
	v_add_f32_e32 v121, 1.0, v121
	v_subbrev_co_u32_e32 v122, vcc, 0, v122, vcc
	v_add_f32_e32 v123, v129, v123
	v_sub_u32_e32 v129, 0, v120
	v_cvt_f32_i32_e32 v120, v120
	v_add_f32_e32 v121, v131, v121
	v_sub_u32_e32 v130, 0, v122
	v_ldexp_f32 v126, v126, v129
	v_ldexp_f32 v123, v123, v129
	v_ldexp_f32 v127, v127, v130
	v_ldexp_f32 v121, v121, v130
	v_add_f32_e32 v129, -1.0, v126
	v_add_f32_e32 v130, 1.0, v126
	v_add_f32_e32 v131, 1.0, v129
	v_add_f32_e32 v132, -1.0, v130
	v_sub_f32_e32 v131, v126, v131
	v_sub_f32_e32 v126, v126, v132
	v_mul_f32_e32 v132, 0x3f317218, v120
	v_add_f32_e32 v131, v123, v131
	v_add_f32_e32 v123, v123, v126
	v_fma_f32 v126, v120, s56, -v132
	v_add_f32_e32 v133, v129, v131
	v_add_f32_e32 v134, v130, v123
	v_fmac_f32_e32 v126, 0xb102e308, v120
	v_sub_f32_e32 v120, v133, v129
	v_sub_f32_e32 v129, v134, v130
	v_rcp_f32_e32 v130, v134
	v_add_f32_e32 v135, v132, v126
	v_sub_f32_e32 v123, v123, v129
	v_sub_f32_e32 v129, v135, v132
	v_sub_f32_e32 v126, v126, v129
	v_mul_f32_e32 v129, v133, v130
	v_sub_f32_e32 v120, v131, v120
	v_mul_f32_e32 v131, v134, v129
	v_fma_f32 v132, v129, v134, -v131
	v_fmac_f32_e32 v132, v129, v123
	v_add_f32_e32 v136, v131, v132
	v_sub_f32_e32 v137, v133, v136
	v_sub_f32_e32 v131, v136, v131
	v_sub_f32_e32 v133, v133, v137
	v_sub_f32_e32 v131, v131, v132
	v_sub_f32_e32 v132, v133, v136
	v_add_f32_e32 v120, v120, v132
	v_add_f32_e32 v120, v131, v120
	v_add_f32_e32 v131, v137, v120
	v_mul_f32_e32 v132, v130, v131
	v_sub_f32_e32 v133, v137, v131
	v_mul_f32_e32 v136, v134, v132
	v_add_f32_e32 v120, v120, v133
	v_add_f32_e32 v133, v129, v132
	v_fma_f32 v134, v132, v134, -v136
	v_sub_f32_e32 v129, v133, v129
	v_fmac_f32_e32 v134, v132, v123
	v_sub_f32_e32 v123, v132, v129
	v_add_f32_e32 v129, v136, v134
	v_sub_f32_e32 v132, v129, v136
	v_sub_f32_e32 v136, v131, v129
	v_sub_f32_e32 v131, v131, v136
	v_sub_f32_e32 v129, v131, v129
	v_sub_f32_e32 v132, v132, v134
	v_add_f32_e32 v120, v120, v129
	v_add_f32_e32 v120, v132, v120
	v_add_f32_e32 v120, v136, v120
	v_mul_f32_e32 v120, v130, v120
	v_add_f32_e32 v120, v123, v120
	v_add_f32_e32 v123, v133, v120
	v_mul_f32_e32 v129, v123, v123
	v_fmamk_f32 v132, v129, 0x3e9b6dac, v112
	v_sub_f32_e32 v130, v123, v133
	v_ldexp_f32 v131, v123, 1
	v_mul_f32_e32 v123, v123, v129
	v_fmaak_f32 v129, v129, v132, 0x3f2aaada
	v_mul_f32_e32 v123, v123, v129
	v_add_f32_e32 v129, v131, v123
	v_sub_f32_e32 v120, v120, v130
	v_sub_f32_e32 v130, v129, v131
	v_ldexp_f32 v120, v120, 1
	v_sub_f32_e32 v123, v123, v130
	v_add_f32_e32 v120, v120, v123
	v_add_f32_e32 v123, v129, v120
	v_sub_f32_e32 v129, v123, v129
	v_add_f32_e32 v130, v135, v123
	v_sub_f32_e32 v120, v120, v129
	v_sub_f32_e32 v129, v130, v135
	v_sub_f32_e32 v131, v130, v129
	v_sub_f32_e32 v123, v123, v129
	v_add_f32_e32 v129, v126, v120
	v_sub_f32_e32 v131, v135, v131
	v_sub_f32_e32 v132, v129, v126
	v_add_f32_e32 v123, v123, v131
	v_sub_f32_e32 v131, v129, v132
	v_sub_f32_e32 v120, v120, v132
	v_sub_f32_e32 v126, v126, v131
	v_add_f32_e32 v123, v129, v123
	v_add_f32_e32 v120, v120, v126
	v_add_f32_e32 v126, v130, v123
	v_sub_f32_e32 v129, v126, v130
	v_sub_f32_e32 v123, v123, v129
	v_add_f32_e32 v120, v120, v123
	v_add_f32_e32 v120, v126, v120
	v_cmp_neq_f32_e32 vcc, s57, v125
	v_add_f32_e32 v123, -1.0, v127
	v_add_f32_e32 v129, 1.0, v127
	v_cndmask_b32_e32 v120, v114, v120, vcc
	v_cmp_ngt_f32_e32 vcc, -1.0, v125
	v_add_f32_e32 v130, -1.0, v129
	v_cvt_f32_i32_e32 v122, v122
	v_cndmask_b32_e32 v120, v115, v120, vcc
	v_cmp_neq_f32_e32 vcc, -1.0, v125
	s_waitcnt vmcnt(3)
	v_add_f32_e32 v16, v16, v117
	v_mul_f32_e32 v16, 0xbfb8aa3b, v16
	v_cndmask_b32_e32 v120, v116, v120, vcc
	v_cmp_lt_f32_e64 vcc, |v125|, s58
	v_exp_f32_e32 v16, v16
	v_cmp_lt_f32_e64 s[0:1], |v128|, s58
	v_cndmask_b32_e32 v120, v120, v125, vcc
	v_add_f32_e32 v125, 1.0, v123
	v_sub_f32_e32 v125, v127, v125
	v_sub_f32_e32 v127, v127, v130
	v_add_f32_e32 v125, v121, v125
	v_add_f32_e32 v121, v121, v127
	v_add_f32_e32 v127, v129, v121
	v_rcp_f32_e32 v130, v127
	v_add_f32_e32 v126, v123, v125
	v_sub_f32_e32 v123, v126, v123
	v_sub_f32_e32 v123, v125, v123
	v_sub_f32_e32 v125, v127, v129
	v_sub_f32_e32 v121, v121, v125
	v_mul_f32_e32 v125, v126, v130
	v_mul_f32_e32 v129, v127, v125
	v_fma_f32 v131, v125, v127, -v129
	v_fmac_f32_e32 v131, v125, v121
	v_add_f32_e32 v132, v129, v131
	v_sub_f32_e32 v133, v126, v132
	v_sub_f32_e32 v126, v126, v133
	v_sub_f32_e32 v129, v132, v129
	v_sub_f32_e32 v126, v126, v132
	v_add_f32_e32 v123, v123, v126
	v_sub_f32_e32 v126, v129, v131
	v_add_f32_e32 v123, v126, v123
	v_add_f32_e32 v126, v133, v123
	v_mul_f32_e32 v129, v130, v126
	v_mul_f32_e32 v131, v127, v129
	v_fma_f32 v127, v129, v127, -v131
	v_fmac_f32_e32 v127, v129, v121
	v_sub_f32_e32 v121, v133, v126
	v_add_f32_e32 v121, v123, v121
	v_add_f32_e32 v123, v131, v127
	v_sub_f32_e32 v132, v126, v123
	v_sub_f32_e32 v126, v126, v132
	v_sub_f32_e32 v131, v123, v131
	v_sub_f32_e32 v123, v126, v123
	v_add_f32_e32 v121, v121, v123
	v_sub_f32_e32 v123, v131, v127
	v_add_f32_e32 v121, v123, v121
	v_add_f32_e32 v123, v125, v129
	v_add_f32_e32 v121, v132, v121
	v_sub_f32_e32 v125, v123, v125
	v_mul_f32_e32 v121, v130, v121
	v_sub_f32_e32 v125, v129, v125
	v_add_f32_e32 v121, v125, v121
	v_mul_f32_e32 v129, 0x3f317218, v122
	v_add_f32_e32 v125, v123, v121
	v_fma_f32 v130, v122, s56, -v129
	v_mul_f32_e32 v126, v125, v125
	v_fmac_f32_e32 v130, 0xb102e308, v122
	v_fmamk_f32 v127, v126, 0x3e9b6dac, v112
	v_sub_f32_e32 v122, v125, v123
	v_add_f32_e32 v131, v129, v130
	v_fmaak_f32 v127, v126, v127, 0x3f2aaada
	v_sub_f32_e32 v121, v121, v122
	v_sub_f32_e32 v122, v131, v129
	v_mul_f32_e32 v123, v125, v126
	v_sub_f32_e32 v129, v130, v122
	v_ldexp_f32 v122, v125, 1
	v_mul_f32_e32 v123, v123, v127
	v_add_f32_e32 v125, v122, v123
	v_sub_f32_e32 v122, v125, v122
	v_ldexp_f32 v121, v121, 1
	v_sub_f32_e32 v122, v123, v122
	v_add_f32_e32 v121, v121, v122
	v_add_f32_e32 v130, v125, v121
	v_sub_f32_e32 v122, v130, v125
	v_sub_f32_e32 v132, v121, v122
	v_lshl_or_b32 v121, s60, 17, v124
	v_add_lshl_u32 v167, v121, v71, 1
	global_load_ushort v134, v167, s[8:9]
	global_load_ushort v135, v167, s[8:9] offset:64
	v_add_lshl_u32 v167, v121, v72, 1
	global_load_ushort v136, v167, s[8:9]
	global_load_ushort v137, v167, s[8:9] offset:64
	v_add_lshl_u32 v167, v121, v73, 1
	global_load_ushort v138, v167, s[8:9]
	global_load_ushort v139, v167, s[8:9] offset:64
	v_add_lshl_u32 v167, v121, v74, 1
	global_load_ushort v140, v167, s[8:9]
	global_load_ushort v141, v167, s[8:9] offset:64
	v_add_lshl_u32 v167, v121, v75, 1
	global_load_ushort v142, v167, s[8:9]
	global_load_ushort v143, v167, s[8:9] offset:64
	v_add_lshl_u32 v167, v121, v76, 1
	global_load_ushort v144, v167, s[8:9]
	global_load_ushort v145, v167, s[8:9] offset:64
	v_add_lshl_u32 v167, v121, v77, 1
	global_load_ushort v146, v167, s[8:9]
	global_load_ushort v147, v167, s[8:9] offset:64
	v_add_lshl_u32 v167, v121, v78, 1
	global_load_ushort v148, v167, s[8:9]
	global_load_ushort v149, v167, s[8:9] offset:64
	v_add_lshl_u32 v167, v121, v79, 1
	global_load_ushort v150, v167, s[8:9]
	global_load_ushort v151, v167, s[8:9] offset:64
	v_add_lshl_u32 v167, v121, v80, 1
	global_load_ushort v152, v167, s[8:9]
	global_load_ushort v153, v167, s[8:9] offset:64
	v_add_lshl_u32 v167, v121, v81, 1
	global_load_ushort v154, v167, s[8:9]
	global_load_ushort v156, v167, s[8:9] offset:64
	v_add_lshl_u32 v167, v121, v82, 1
	global_load_ushort v157, v167, s[8:9]
	global_load_ushort v158, v167, s[8:9] offset:64
	v_add_lshl_u32 v167, v121, v83, 1
	global_load_ushort v159, v167, s[8:9]
	global_load_ushort v160, v167, s[8:9] offset:64
	v_add_lshl_u32 v167, v121, v84, 1
	global_load_ushort v161, v167, s[8:9]
	global_load_ushort v162, v167, s[8:9] offset:64
	v_add_lshl_u32 v167, v121, v85, 1
	global_load_ushort v163, v167, s[8:9]
	global_load_ushort v164, v167, s[8:9] offset:64
	v_add_lshl_u32 v167, v121, v86, 1
	global_load_ushort v165, v167, s[8:9]
	global_load_ushort v166, v167, s[8:9] offset:64
	s_waitcnt vmcnt(0)
	v_add_u32_e32 v122, v121, v71
	v_ashrrev_i32_e32 v123, 31, v122
	v_lshlrev_b64 v[124:125], 1, v[122:123]
	v_lshl_add_u64 v[126:127], s[8:9], 0, v[124:125]
	v_mov_b32_e32 v126, v134
	v_add_f32_e32 v123, v131, v130
	v_sub_f32_e32 v127, v123, v131
	v_sub_f32_e32 v133, v123, v127
	v_sub_f32_e32 v131, v131, v133
	v_sub_f32_e32 v127, v130, v127
	v_add_f32_e32 v130, v129, v132
	v_add_f32_e32 v127, v127, v131
	v_sub_f32_e32 v131, v130, v129
	v_sub_f32_e32 v133, v130, v131
	v_add_f32_e32 v127, v130, v127
	v_sub_f32_e32 v129, v129, v133
	v_sub_f32_e32 v131, v132, v131
	v_add_f32_e32 v130, v123, v127
	v_or_b32_e32 v122, 32, v122
	v_add_f32_e32 v129, v131, v129
	v_sub_f32_e32 v131, v130, v123
	v_ashrrev_i32_e32 v123, 31, v122
	v_lshl_add_u64 v[122:123], v[122:123], 1, s[8:9]
	v_mov_b32_e32 v122, v135
	v_add_f32_e32 v16, 1.0, v16
	v_rcp_f32_e32 v16, v16
	v_mul_f32_e32 v120, 0xc1000000, v120
	v_sub_f32_e32 v123, v127, v131
	v_add_f32_e32 v123, v129, v123
	v_mul_f32_e32 v127, v16, v120
	v_add_f32_e32 v16, v32, v118
	v_mul_f32_e32 v16, 0xbfb8aa3b, v16
	v_add_f32_e32 v32, v127, v127
	v_exp_f32_e32 v16, v16
	v_mul_f32_e32 v32, 0x3fb8aa3b, v32
	v_exp_f32_e32 v32, v32
	v_add_f32_e32 v123, v130, v123
	v_cmp_neq_f32_e32 vcc, s57, v128
	v_add_f32_e32 v16, 1.0, v16
	v_rcp_f32_e32 v129, v16
	v_cndmask_b32_e32 v123, v114, v123, vcc
	v_cmp_ngt_f32_e32 vcc, -1.0, v128
	v_sub_f32_e32 v16, 1.0, v32
	v_max_f32_e32 v16, 0, v16
	v_cndmask_b32_e32 v123, v115, v123, vcc
	v_cmp_neq_f32_e32 vcc, -1.0, v128
	v_mul_f32_e32 v32, 0x4f800000, v16
	v_add_f32_e32 v48, v48, v119
	v_cndmask_b32_e32 v123, v116, v123, vcc
	v_cmp_gt_f32_e32 vcc, s59, v16
	v_mul_f32_e32 v48, 0xbfb8aa3b, v48
	v_exp_f32_e32 v48, v48
	v_cndmask_b32_e32 v32, v16, v32, vcc
	v_sqrt_f32_e32 v130, v32
	v_cndmask_b32_e64 v16, v123, v128, s[0:1]
	v_mul_f32_e32 v16, 0xc1000000, v16
	v_mul_f32_e32 v128, v129, v16
	v_add_u32_e32 v123, -1, v130
	v_fma_f32 v129, -v123, v130, v32
	v_cmp_ge_f32_e64 s[0:1], 0, v129
	v_add_u32_e32 v129, 1, v130
	v_add_f32_e32 v48, 1.0, v48
	v_cndmask_b32_e64 v123, v130, v123, s[0:1]
	v_fma_f32 v130, -v129, v130, v32
	v_cmp_lt_f32_e64 s[0:1], 0, v130
	v_rcp_f32_e32 v48, v48
	v_add_f32_e32 v0, v0, v68
	v_cndmask_b32_e64 v123, v123, v129, s[0:1]
	v_mul_f32_e32 v129, 0x37800000, v123
	v_cndmask_b32_e32 v123, v123, v129, vcc
	v_add_f32_e32 v129, v128, v128
	v_mul_f32_e32 v129, 0x3fb8aa3b, v129
	v_exp_f32_e32 v129, v129
	v_cmp_class_f32_e32 vcc, v32, v113
	v_mul_f32_e32 v0, 0xbfb8aa3b, v0
	v_exp_f32_e32 v0, v0
	v_cndmask_b32_e32 v32, v123, v32, vcc
	v_sub_f32_e32 v123, 1.0, v129
	v_max_f32_e32 v123, 0, v123
	v_mul_f32_e32 v129, 0x4f800000, v123
	v_cmp_gt_f32_e32 vcc, s59, v123
	v_mul_f32_e32 v32, v48, v32
	v_add_f32_e32 v0, 1.0, v0
	v_cndmask_b32_e32 v123, v123, v129, vcc
	v_sqrt_f32_e32 v129, v123
	v_lshlrev_b32_e32 v48, 16, v126
	v_mul_f32_e32 v32, v32, v48
	v_rcp_f32_e32 v0, v0
	v_add_u32_e32 v48, -1, v129
	v_fma_f32 v126, -v48, v129, v123
	v_cmp_ge_f32_e64 s[0:1], 0, v126
	v_add_u32_e32 v126, 1, v129
	v_add_f32_e32 v17, v17, v117
	v_cndmask_b32_e64 v48, v129, v48, s[0:1]
	v_fma_f32 v129, -v126, v129, v123
	v_cmp_lt_f32_e64 s[0:1], 0, v129
	v_mul_f32_e32 v17, 0xbfb8aa3b, v17
	v_exp_f32_e32 v17, v17
	v_cndmask_b32_e64 v48, v48, v126, s[0:1]
	v_mul_f32_e32 v126, 0x37800000, v48
	v_cndmask_b32_e32 v48, v48, v126, vcc
	v_cmp_class_f32_e32 vcc, v123, v113
	v_cvt_pk_bf16_f32 v32, v32, s0
	v_add_f32_e32 v17, 1.0, v17
	v_cndmask_b32_e32 v48, v48, v123, vcc
	v_mul_f32_e32 v0, v0, v48
	v_lshlrev_b32_e32 v48, 16, v122
	v_mul_f32_e32 v0, v0, v48
	v_cvt_pk_bf16_f32 v48, v127, s0
	v_lshl_add_u64 v[122:123], s[48:49], 0, v[124:125]
	global_store_short v[122:123], v48, off sc1
	v_cvt_pk_bf16_f32 v48, v128, s0
	global_store_short v[122:123], v48, off offset:64 sc1
	v_lshl_add_u64 v[122:123], s[46:47], 0, v[124:125]
	v_cvt_pk_bf16_f32 v0, v0, s0
	global_store_short v[122:123], v32, off sc1
	global_store_short v[122:123], v0, off offset:64 sc1
	v_add_u32_e32 v122, v121, v72
	v_ashrrev_i32_e32 v123, 31, v122
	v_lshlrev_b64 v[124:125], 1, v[122:123]
	v_lshl_add_u64 v[126:127], s[8:9], 0, v[124:125]
	v_mov_b32_e32 v0, v136
	v_or_b32_e32 v122, 32, v122
	v_ashrrev_i32_e32 v123, 31, v122
	v_lshl_add_u64 v[122:123], v[122:123], 1, s[8:9]
	v_mov_b32_e32 v32, v137
	v_rcp_f32_e32 v17, v17
	v_add_f32_e32 v33, v33, v118
	v_mul_f32_e32 v33, 0xbfb8aa3b, v33
	v_exp_f32_e32 v33, v33
	v_mul_f32_e32 v17, v17, v120
	v_add_f32_e32 v48, v17, v17
	v_mul_f32_e32 v48, 0x3fb8aa3b, v48
	v_exp_f32_e32 v48, v48
	v_add_f32_e32 v33, 1.0, v33
	v_rcp_f32_e32 v33, v33
	v_add_f32_e32 v49, v49, v119
	v_sub_f32_e32 v48, 1.0, v48
	v_max_f32_e32 v48, 0, v48
	v_mul_f32_e32 v122, 0x4f800000, v48
	v_cmp_gt_f32_e32 vcc, s59, v48
	v_mul_f32_e32 v33, v33, v16
	v_mul_f32_e32 v49, 0xbfb8aa3b, v49
	v_cndmask_b32_e32 v48, v48, v122, vcc
	v_sqrt_f32_e32 v122, v48
	v_exp_f32_e32 v49, v49
	v_add_f32_e32 v1, v1, v68
	v_mul_f32_e32 v1, 0xbfb8aa3b, v1
	v_add_u32_e32 v123, -1, v122
	v_fma_f32 v126, -v123, v122, v48
	v_cmp_ge_f32_e64 s[0:1], 0, v126
	v_add_u32_e32 v126, 1, v122
	v_add_f32_e32 v49, 1.0, v49
	v_cndmask_b32_e64 v123, v122, v123, s[0:1]
	v_fma_f32 v122, -v126, v122, v48
	v_cmp_lt_f32_e64 s[0:1], 0, v122
	v_rcp_f32_e32 v49, v49
	v_exp_f32_e32 v1, v1
	v_cndmask_b32_e64 v122, v123, v126, s[0:1]
	v_mul_f32_e32 v123, 0x37800000, v122
	v_cndmask_b32_e32 v122, v122, v123, vcc
	v_add_f32_e32 v123, v33, v33
	v_mul_f32_e32 v123, 0x3fb8aa3b, v123
	v_exp_f32_e32 v123, v123
	v_cmp_class_f32_e32 vcc, v48, v113
	v_add_f32_e32 v1, 1.0, v1
	v_rcp_f32_e32 v1, v1
	v_cndmask_b32_e32 v48, v122, v48, vcc
	v_sub_f32_e32 v122, 1.0, v123
	v_max_f32_e32 v122, 0, v122
	v_mul_f32_e32 v123, 0x4f800000, v122
	v_cmp_gt_f32_e32 vcc, s59, v122
	v_mul_f32_e32 v48, v49, v48
	v_add_f32_e32 v2, v2, v68
	v_cndmask_b32_e32 v122, v122, v123, vcc
	v_sqrt_f32_e32 v123, v122
	v_mul_f32_e32 v2, 0xbfb8aa3b, v2
	v_exp_f32_e32 v2, v2
	v_add_f32_e32 v3, v3, v68
	v_mul_f32_e32 v3, 0xbfb8aa3b, v3
	v_exp_f32_e32 v3, v3
	v_add_f32_e32 v2, 1.0, v2
	v_rcp_f32_e32 v2, v2
	v_add_f32_e32 v3, 1.0, v3
	v_rcp_f32_e32 v3, v3
	v_lshlrev_b32_e32 v0, 16, v0
	v_mul_f32_e32 v48, v48, v0
	v_add_u32_e32 v0, -1, v123
	v_fma_f32 v49, -v0, v123, v122
	v_cmp_ge_f32_e64 s[0:1], 0, v49
	v_add_u32_e32 v49, 1, v123
	s_nop 0
	v_cndmask_b32_e64 v0, v123, v0, s[0:1]
	v_fma_f32 v123, -v49, v123, v122
	v_cmp_lt_f32_e64 s[0:1], 0, v123
	s_nop 1
	v_cndmask_b32_e64 v0, v0, v49, s[0:1]
	v_mul_f32_e32 v49, 0x37800000, v0
	v_cndmask_b32_e32 v0, v0, v49, vcc
	v_cmp_class_f32_e32 vcc, v122, v113
	v_cvt_pk_bf16_f32 v17, v17, s0
	s_nop 0
	v_cndmask_b32_e32 v0, v0, v122, vcc
	v_mul_f32_e32 v0, v1, v0
	v_lshlrev_b32_e32 v1, 16, v32
	v_mul_f32_e32 v32, v0, v1
	v_lshl_add_u64 v[0:1], s[48:49], 0, v[124:125]
	global_store_short v[0:1], v17, off sc1
	v_cvt_pk_bf16_f32 v17, v33, s0
	global_store_short v[0:1], v17, off offset:64 sc1
	v_cvt_pk_bf16_f32 v17, v48, s0
	v_lshl_add_u64 v[0:1], s[46:47], 0, v[124:125]
	global_store_short v[0:1], v17, off sc1
	v_cvt_pk_bf16_f32 v17, v32, s0
	global_store_short v[0:1], v17, off offset:64 sc1
	v_add_u32_e32 v0, v121, v73
	v_ashrrev_i32_e32 v1, 31, v0
	v_lshlrev_b64 v[32:33], 1, v[0:1]
	v_lshl_add_u64 v[48:49], s[8:9], 0, v[32:33]
	v_mov_b32_e32 v17, v138
	v_or_b32_e32 v0, 32, v0
	v_ashrrev_i32_e32 v1, 31, v0
	v_lshl_add_u64 v[0:1], v[0:1], 1, s[8:9]
	v_mov_b32_e32 v0, v139
	v_add_f32_e32 v1, v18, v117
	v_mul_f32_e32 v1, 0xbfb8aa3b, v1
	v_exp_f32_e32 v1, v1
	v_add_f32_e32 v18, v34, v118
	v_mul_f32_e32 v18, 0xbfb8aa3b, v18
	v_exp_f32_e32 v18, v18
	v_add_f32_e32 v1, 1.0, v1
	v_rcp_f32_e32 v1, v1
	v_add_f32_e32 v18, 1.0, v18
	v_rcp_f32_e32 v18, v18
	v_mul_f32_e32 v1, v1, v120
	v_add_f32_e32 v34, v1, v1
	v_mul_f32_e32 v34, 0x3fb8aa3b, v34
	v_exp_f32_e32 v34, v34
	v_mul_f32_e32 v18, v18, v16
	v_sub_f32_e32 v34, 1.0, v34
	v_max_f32_e32 v34, 0, v34
	v_mul_f32_e32 v48, 0x4f800000, v34
	v_cmp_gt_f32_e32 vcc, s59, v34
	v_lshlrev_b32_e32 v17, 16, v17
	v_cndmask_b32_e32 v34, v34, v48, vcc
	v_sqrt_f32_e32 v48, v34
	v_lshlrev_b32_e32 v0, 16, v0
	v_add_u32_e32 v49, -1, v48
	v_fma_f32 v122, -v49, v48, v34
	v_cmp_ge_f32_e64 s[0:1], 0, v122
	v_add_u32_e32 v122, 1, v48
	s_nop 0
	v_cndmask_b32_e64 v49, v48, v49, s[0:1]
	v_fma_f32 v48, -v122, v48, v34
	v_cmp_lt_f32_e64 s[0:1], 0, v48
	s_nop 1
	v_cndmask_b32_e64 v48, v49, v122, s[0:1]
	v_mul_f32_e32 v49, 0x37800000, v48
	v_cndmask_b32_e32 v48, v48, v49, vcc
	v_add_f32_e32 v49, v50, v119
	v_add_f32_e32 v50, v18, v18
	v_mul_f32_e32 v49, 0xbfb8aa3b, v49
	v_mul_f32_e32 v50, 0x3fb8aa3b, v50
	v_exp_f32_e32 v49, v49
	v_exp_f32_e32 v50, v50
	v_cmp_class_f32_e32 vcc, v34, v113
	s_nop 1
	v_cndmask_b32_e32 v34, v48, v34, vcc
	v_add_f32_e32 v48, 1.0, v49
	v_sub_f32_e32 v49, 1.0, v50
	v_max_f32_e32 v49, 0, v49
	v_mul_f32_e32 v50, 0x4f800000, v49
	v_cmp_gt_f32_e32 vcc, s59, v49
	v_rcp_f32_e32 v48, v48
	s_nop 0
	v_cndmask_b32_e32 v49, v49, v50, vcc
	v_sqrt_f32_e32 v50, v49
	v_mul_f32_e32 v34, v48, v34
	v_mul_f32_e32 v17, v34, v17
	v_add_u32_e32 v34, -1, v50
	v_fma_f32 v48, -v34, v50, v49
	v_cmp_ge_f32_e64 s[0:1], 0, v48
	v_add_u32_e32 v48, 1, v50
	s_nop 0
	v_cndmask_b32_e64 v34, v50, v34, s[0:1]
	v_fma_f32 v50, -v48, v50, v49
	v_cmp_lt_f32_e64 s[0:1], 0, v50
	s_nop 1
	v_cndmask_b32_e64 v34, v34, v48, s[0:1]
	v_mul_f32_e32 v48, 0x37800000, v34
	v_cndmask_b32_e32 v34, v34, v48, vcc
	v_cmp_class_f32_e32 vcc, v49, v113
	v_cvt_pk_bf16_f32 v18, v18, s0
	v_cvt_pk_bf16_f32 v17, v17, s0
	v_cndmask_b32_e32 v34, v34, v49, vcc
	v_mul_f32_e32 v2, v2, v34
	v_mul_f32_e32 v2, v2, v0
	v_cvt_pk_bf16_f32 v34, v1, s0
	v_lshl_add_u64 v[0:1], s[48:49], 0, v[32:33]
	global_store_short v[0:1], v34, off sc1
	global_store_short v[0:1], v18, off offset:64 sc1
	v_lshl_add_u64 v[0:1], s[46:47], 0, v[32:33]
	v_cvt_pk_bf16_f32 v2, v2, s0
	global_store_short v[0:1], v17, off sc1
	global_store_short v[0:1], v2, off offset:64 sc1
	v_add_u32_e32 v0, v121, v74
	v_ashrrev_i32_e32 v1, 31, v0
	v_lshlrev_b64 v[32:33], 1, v[0:1]
	v_lshl_add_u64 v[48:49], s[8:9], 0, v[32:33]
	v_mov_b32_e32 v2, v140
	v_or_b32_e32 v0, 32, v0
	v_ashrrev_i32_e32 v1, 31, v0
	v_lshl_add_u64 v[0:1], v[0:1], 1, s[8:9]
	v_mov_b32_e32 v0, v141
	v_add_f32_e32 v1, v19, v117
	v_mul_f32_e32 v1, 0xbfb8aa3b, v1
	v_exp_f32_e32 v1, v1
	v_add_f32_e32 v17, v35, v118
	v_mul_f32_e32 v17, 0xbfb8aa3b, v17
	v_exp_f32_e32 v17, v17
	v_add_f32_e32 v1, 1.0, v1
	v_rcp_f32_e32 v1, v1
	v_add_f32_e32 v17, 1.0, v17
	v_rcp_f32_e32 v17, v17
	v_mul_f32_e32 v1, v1, v120
	v_add_f32_e32 v18, v1, v1
	v_mul_f32_e32 v18, 0x3fb8aa3b, v18
	v_exp_f32_e32 v18, v18
	v_mul_f32_e32 v17, v17, v16
	v_sub_f32_e32 v18, 1.0, v18
	v_max_f32_e32 v18, 0, v18
	v_mul_f32_e32 v19, 0x4f800000, v18
	v_cmp_gt_f32_e32 vcc, s59, v18
	v_lshlrev_b32_e32 v2, 16, v2
	v_cndmask_b32_e32 v18, v18, v19, vcc
	v_sqrt_f32_e32 v19, v18
	v_lshlrev_b32_e32 v0, 16, v0
	v_add_u32_e32 v34, -1, v19
	v_fma_f32 v35, -v34, v19, v18
	v_cmp_ge_f32_e64 s[0:1], 0, v35
	v_add_u32_e32 v35, 1, v19
	s_nop 0
	v_cndmask_b32_e64 v34, v19, v34, s[0:1]
	v_fma_f32 v19, -v35, v19, v18
	v_cmp_lt_f32_e64 s[0:1], 0, v19
	s_nop 1
	v_cndmask_b32_e64 v19, v34, v35, s[0:1]
	v_mul_f32_e32 v34, 0x37800000, v19
	v_cndmask_b32_e32 v19, v19, v34, vcc
	v_add_f32_e32 v34, v51, v119
	v_add_f32_e32 v35, v17, v17
	v_mul_f32_e32 v34, 0xbfb8aa3b, v34
	v_mul_f32_e32 v35, 0x3fb8aa3b, v35
	v_exp_f32_e32 v34, v34
	v_exp_f32_e32 v35, v35
	v_cmp_class_f32_e32 vcc, v18, v113
	s_nop 1
	v_cndmask_b32_e32 v18, v19, v18, vcc
	v_add_f32_e32 v19, 1.0, v34
	v_sub_f32_e32 v34, 1.0, v35
	v_max_f32_e32 v34, 0, v34
	v_mul_f32_e32 v35, 0x4f800000, v34
	v_cmp_gt_f32_e32 vcc, s59, v34
	v_rcp_f32_e32 v19, v19
	s_nop 0
	v_cndmask_b32_e32 v34, v34, v35, vcc
	v_sqrt_f32_e32 v35, v34
	v_mul_f32_e32 v18, v19, v18
	v_mul_f32_e32 v2, v18, v2
	v_add_u32_e32 v18, -1, v35
	v_fma_f32 v19, -v18, v35, v34
	v_cmp_ge_f32_e64 s[0:1], 0, v19
	v_add_u32_e32 v19, 1, v35
	s_nop 0
	v_cndmask_b32_e64 v18, v35, v18, s[0:1]
	v_fma_f32 v35, -v19, v35, v34
	v_cmp_lt_f32_e64 s[0:1], 0, v35
	s_nop 1
	v_cndmask_b32_e64 v18, v18, v19, s[0:1]
	v_mul_f32_e32 v19, 0x37800000, v18
	v_cndmask_b32_e32 v18, v18, v19, vcc
	v_cmp_class_f32_e32 vcc, v34, v113
	v_cvt_pk_bf16_f32 v17, v17, s0
	v_cvt_pk_bf16_f32 v2, v2, s0
	v_cndmask_b32_e32 v18, v18, v34, vcc
	v_mul_f32_e32 v3, v3, v18
	v_mul_f32_e32 v3, v3, v0
	v_cvt_pk_bf16_f32 v18, v1, s0
	v_lshl_add_u64 v[0:1], s[48:49], 0, v[32:33]
	global_store_short v[0:1], v18, off sc1
	global_store_short v[0:1], v17, off offset:64 sc1
	v_lshl_add_u64 v[0:1], s[46:47], 0, v[32:33]
	global_store_short v[0:1], v2, off sc1
	v_cvt_pk_bf16_f32 v2, v3, s0
	global_store_short v[0:1], v2, off offset:64 sc1
	v_add_u32_e32 v0, v121, v75
	v_ashrrev_i32_e32 v1, 31, v0
	v_lshlrev_b64 v[2:3], 1, v[0:1]
	v_or_b32_e32 v0, 32, v0
	v_lshl_add_u64 v[18:19], s[8:9], 0, v[2:3]
	v_ashrrev_i32_e32 v1, 31, v0
	v_lshl_add_u64 v[0:1], v[0:1], 1, s[8:9]
	v_mov_b32_e32 v17, v142
	s_nop 0
	v_mov_b32_e32 v18, v143
	v_add_f32_e32 v0, v20, v117
	v_add_f32_e32 v1, v36, v118
	v_mul_f32_e32 v0, 0xbfb8aa3b, v0
	v_mul_f32_e32 v1, 0xbfb8aa3b, v1
	v_exp_f32_e32 v20, v0
	v_exp_f32_e32 v32, v1
	v_lshl_add_u64 v[0:1], s[48:49], 0, v[2:3]
	v_add_f32_e32 v19, v52, v119
	v_add_f32_e32 v20, 1.0, v20
	v_add_f32_e32 v32, 1.0, v32
	v_rcp_f32_e32 v20, v20
	v_rcp_f32_e32 v32, v32
	v_add_f32_e32 v4, v4, v68
	v_mul_f32_e32 v19, 0xbfb8aa3b, v19
	v_mul_f32_e32 v20, v20, v120
	v_mul_f32_e32 v32, v32, v16
	v_add_f32_e32 v33, v20, v20
	v_add_f32_e32 v34, v32, v32
	v_mul_f32_e32 v33, 0x3fb8aa3b, v33
	v_mul_f32_e32 v34, 0x3fb8aa3b, v34
	v_exp_f32_e32 v33, v33
	v_exp_f32_e32 v34, v34
	v_cvt_pk_bf16_f32 v20, v20, s0
	global_store_short v[0:1], v20, off sc1
	v_sub_f32_e32 v20, 1.0, v33
	v_sub_f32_e32 v33, 1.0, v34
	v_max_f32_e32 v20, 0, v20
	v_max_f32_e32 v33, 0, v33
	v_mul_f32_e32 v34, 0x4f800000, v20
	v_cmp_gt_f32_e32 vcc, s59, v20
	v_cvt_pk_bf16_f32 v32, v32, s0
	v_mul_f32_e32 v35, 0x4f800000, v33
	v_cndmask_b32_e32 v20, v20, v34, vcc
	v_cmp_gt_f32_e64 s[0:1], s59, v33
	v_sqrt_f32_e32 v34, v20
	v_mul_f32_e32 v4, 0xbfb8aa3b, v4
	v_cndmask_b32_e64 v33, v33, v35, s[0:1]
	v_sqrt_f32_e32 v35, v33
	global_store_short v[0:1], v32, off offset:64 sc1
	v_add_u32_e32 v0, -1, v34
	v_exp_f32_e32 v19, v19
	v_exp_f32_e32 v4, v4
	v_add_u32_e32 v32, -1, v35
	v_fma_f32 v48, -v0, v34, v20
	v_add_u32_e32 v1, 1, v34
	v_fma_f32 v50, -v32, v35, v33
	v_cmp_ge_f32_e64 s[4:5], 0, v48
	v_add_u32_e32 v36, 1, v35
	v_fma_f32 v49, -v1, v34, v20
	v_cndmask_b32_e64 v0, v34, v0, s[4:5]
	v_cmp_ge_f32_e64 s[4:5], 0, v50
	v_fma_f32 v51, -v36, v35, v33
	v_add_f32_e32 v19, 1.0, v19
	v_cndmask_b32_e64 v32, v35, v32, s[4:5]
	v_cmp_lt_f32_e64 s[4:5], 0, v49
	v_add_f32_e32 v4, 1.0, v4
	v_rcp_f32_e32 v19, v19
	v_cndmask_b32_e64 v0, v0, v1, s[4:5]
	v_cmp_lt_f32_e64 s[4:5], 0, v51
	v_rcp_f32_e32 v4, v4
	v_lshl_add_u64 v[2:3], s[46:47], 0, v[2:3]
	v_cndmask_b32_e64 v1, v32, v36, s[4:5]
	v_mul_f32_e32 v32, 0x37800000, v0
	v_mul_f32_e32 v34, 0x37800000, v1
	v_cndmask_b32_e32 v0, v0, v32, vcc
	v_cmp_class_f32_e32 vcc, v20, v113
	v_cndmask_b32_e64 v1, v1, v34, s[0:1]
	v_add_f32_e32 v5, v5, v68
	v_cndmask_b32_e32 v0, v0, v20, vcc
	v_cmp_class_f32_e32 vcc, v33, v113
	v_mul_f32_e32 v0, v19, v0
	v_mul_f32_e32 v5, 0xbfb8aa3b, v5
	v_cndmask_b32_e32 v1, v1, v33, vcc
	v_mul_f32_e32 v1, v4, v1
	v_exp_f32_e32 v5, v5
	v_add_f32_e32 v6, v6, v68
	v_mul_f32_e32 v6, 0xbfb8aa3b, v6
	v_exp_f32_e32 v6, v6
	v_lshlrev_b32_e32 v4, 16, v17
	v_lshlrev_b32_e32 v17, 16, v18
	v_mul_f32_e32 v0, v0, v4
	v_mul_f32_e32 v1, v1, v17
	v_cvt_pk_bf16_f32 v0, v0, s0
	v_cvt_pk_bf16_f32 v1, v1, s0
	global_store_short v[2:3], v0, off sc1
	global_store_short v[2:3], v1, off offset:64 sc1
	v_add_u32_e32 v0, v121, v76
	v_ashrrev_i32_e32 v1, 31, v0
	v_lshlrev_b64 v[2:3], 1, v[0:1]
	v_or_b32_e32 v0, 32, v0
	v_lshl_add_u64 v[18:19], s[8:9], 0, v[2:3]
	v_ashrrev_i32_e32 v1, 31, v0
	v_lshl_add_u64 v[0:1], v[0:1], 1, s[8:9]
	v_mov_b32_e32 v4, v144
	v_mov_b32_e32 v17, v145
	v_add_f32_e32 v0, v21, v117
	v_add_f32_e32 v1, v37, v118
	v_mul_f32_e32 v0, 0xbfb8aa3b, v0
	v_mul_f32_e32 v1, 0xbfb8aa3b, v1
	v_exp_f32_e32 v19, v0
	v_exp_f32_e32 v20, v1
	v_add_f32_e32 v18, v53, v119
	v_mul_f32_e32 v18, 0xbfb8aa3b, v18
	v_add_f32_e32 v19, 1.0, v19
	v_add_f32_e32 v20, 1.0, v20
	v_rcp_f32_e32 v19, v19
	v_rcp_f32_e32 v20, v20
	v_exp_f32_e32 v18, v18
	v_add_f32_e32 v5, 1.0, v5
	v_mul_f32_e32 v19, v19, v120
	v_mul_f32_e32 v20, v20, v16
	v_add_f32_e32 v21, v19, v19
	v_add_f32_e32 v32, v20, v20
	v_mul_f32_e32 v21, 0x3fb8aa3b, v21
	v_mul_f32_e32 v32, 0x3fb8aa3b, v32
	v_exp_f32_e32 v21, v21
	v_exp_f32_e32 v32, v32
	v_add_f32_e32 v18, 1.0, v18
	v_rcp_f32_e32 v18, v18
	v_sub_f32_e32 v21, 1.0, v21
	v_sub_f32_e32 v32, 1.0, v32
	v_max_f32_e32 v21, 0, v21
	v_max_f32_e32 v32, 0, v32
	v_mul_f32_e32 v33, 0x4f800000, v21
	v_cmp_gt_f32_e32 vcc, s59, v21
	v_mul_f32_e32 v34, 0x4f800000, v32
	v_cmp_gt_f32_e64 s[0:1], s59, v32
	v_cndmask_b32_e32 v21, v21, v33, vcc
	v_sqrt_f32_e32 v33, v21
	v_cndmask_b32_e64 v32, v32, v34, s[0:1]
	v_sqrt_f32_e32 v34, v32
	v_rcp_f32_e32 v5, v5
	v_add_u32_e32 v35, -1, v33
	v_fma_f32 v49, -v35, v33, v21
	v_add_u32_e32 v37, -1, v34
	v_add_u32_e32 v36, 1, v33
	v_fma_f32 v51, -v37, v34, v32
	v_cmp_ge_f32_e64 s[4:5], 0, v49
	v_add_u32_e32 v48, 1, v34
	v_fma_f32 v50, -v36, v33, v21
	v_cndmask_b32_e64 v33, v33, v35, s[4:5]
	v_cmp_ge_f32_e64 s[4:5], 0, v51
	v_fma_f32 v52, -v48, v34, v32
	v_lshl_add_u64 v[0:1], s[48:49], 0, v[2:3]
	v_cndmask_b32_e64 v34, v34, v37, s[4:5]
	v_cmp_lt_f32_e64 s[4:5], 0, v50
	v_cvt_pk_bf16_f32 v19, v19, s0
	global_store_short v[0:1], v19, off sc1
	v_cndmask_b32_e64 v33, v33, v36, s[4:5]
	v_cmp_lt_f32_e64 s[4:5], 0, v52
	v_mul_f32_e32 v35, 0x37800000, v33
	v_cndmask_b32_e32 v33, v33, v35, vcc
	v_cndmask_b32_e64 v34, v34, v48, s[4:5]
	v_mul_f32_e32 v36, 0x37800000, v34
	v_cmp_class_f32_e32 vcc, v21, v113
	v_cndmask_b32_e64 v34, v34, v36, s[0:1]
	v_add_f32_e32 v6, 1.0, v6
	v_cndmask_b32_e32 v21, v33, v21, vcc
	v_cmp_class_f32_e32 vcc, v32, v113
	v_mul_f32_e32 v18, v18, v21
	v_rcp_f32_e32 v6, v6
	v_cndmask_b32_e32 v32, v34, v32, vcc
	v_mul_f32_e32 v5, v5, v32
	v_add_f32_e32 v7, v7, v68
	v_mul_f32_e32 v7, 0xbfb8aa3b, v7
	v_exp_f32_e32 v7, v7
	v_lshlrev_b32_e32 v4, 16, v4
	v_lshlrev_b32_e32 v17, 16, v17
	v_mul_f32_e32 v4, v18, v4
	v_mul_f32_e32 v5, v5, v17
	v_cvt_pk_bf16_f32 v17, v20, s0
	global_store_short v[0:1], v17, off offset:64 sc1
	v_cvt_pk_bf16_f32 v4, v4, s0
	v_lshl_add_u64 v[0:1], s[46:47], 0, v[2:3]
	v_cvt_pk_bf16_f32 v2, v5, s0
	global_store_short v[0:1], v4, off sc1
	global_store_short v[0:1], v2, off offset:64 sc1
	v_add_u32_e32 v0, v121, v77
	v_ashrrev_i32_e32 v1, 31, v0
	v_lshlrev_b64 v[2:3], 1, v[0:1]
	v_or_b32_e32 v0, 32, v0
	v_ashrrev_i32_e32 v1, 31, v0
	v_lshl_add_u64 v[4:5], s[8:9], 0, v[2:3]
	v_lshl_add_u64 v[0:1], v[0:1], 1, s[8:9]
	v_mov_b32_e32 v4, v146
	v_add_f32_e32 v17, v54, v119
	v_mov_b32_e32 v0, v147
	v_add_f32_e32 v1, v22, v117
	v_add_f32_e32 v5, v38, v118
	v_mul_f32_e32 v1, 0xbfb8aa3b, v1
	v_mul_f32_e32 v5, 0xbfb8aa3b, v5
	v_exp_f32_e32 v1, v1
	v_exp_f32_e32 v5, v5
	v_mul_f32_e32 v17, 0xbfb8aa3b, v17
	v_exp_f32_e32 v17, v17
	v_add_f32_e32 v1, 1.0, v1
	v_add_f32_e32 v5, 1.0, v5
	v_rcp_f32_e32 v1, v1
	v_rcp_f32_e32 v5, v5
	v_add_f32_e32 v17, 1.0, v17
	v_rcp_f32_e32 v17, v17
	v_mul_f32_e32 v1, v1, v120
	v_mul_f32_e32 v5, v5, v16
	v_add_f32_e32 v18, v1, v1
	v_add_f32_e32 v19, v5, v5
	v_mul_f32_e32 v18, 0x3fb8aa3b, v18
	v_mul_f32_e32 v19, 0x3fb8aa3b, v19
	v_exp_f32_e32 v18, v18
	v_exp_f32_e32 v19, v19
	v_sub_f32_e32 v18, 1.0, v18
	v_sub_f32_e32 v19, 1.0, v19
	v_max_f32_e32 v18, 0, v18
	v_max_f32_e32 v19, 0, v19
	v_mul_f32_e32 v20, 0x4f800000, v18
	v_cmp_gt_f32_e32 vcc, s59, v18
	v_mul_f32_e32 v21, 0x4f800000, v19
	v_cmp_gt_f32_e64 s[0:1], s59, v19
	v_cndmask_b32_e32 v18, v18, v20, vcc
	v_sqrt_f32_e32 v20, v18
	v_cndmask_b32_e64 v19, v19, v21, s[0:1]
	v_sqrt_f32_e32 v21, v19
	v_cvt_pk_bf16_f32 v5, v5, s0
	v_add_u32_e32 v22, -1, v20
	v_fma_f32 v35, -v22, v20, v18
	v_add_u32_e32 v33, -1, v21
	v_add_u32_e32 v32, 1, v20
	v_fma_f32 v37, -v33, v21, v19
	v_cmp_ge_f32_e64 s[4:5], 0, v35
	v_add_u32_e32 v34, 1, v21
	v_fma_f32 v36, -v32, v20, v18
	v_cndmask_b32_e64 v20, v20, v22, s[4:5]
	v_cmp_ge_f32_e64 s[4:5], 0, v37
	v_fma_f32 v38, -v34, v21, v19
	v_lshlrev_b32_e32 v4, 16, v4
	v_cndmask_b32_e64 v21, v21, v33, s[4:5]
	v_cmp_lt_f32_e64 s[4:5], 0, v36
	v_lshlrev_b32_e32 v0, 16, v0
	v_cndmask_b32_e64 v20, v20, v32, s[4:5]
	v_cmp_lt_f32_e64 s[4:5], 0, v38
	v_mul_f32_e32 v22, 0x37800000, v20
	v_cndmask_b32_e32 v20, v20, v22, vcc
	v_cndmask_b32_e64 v21, v21, v34, s[4:5]
	v_mul_f32_e32 v32, 0x37800000, v21
	v_cmp_class_f32_e32 vcc, v18, v113
	v_cndmask_b32_e64 v21, v21, v32, s[0:1]
	s_nop 0
	v_cndmask_b32_e32 v18, v20, v18, vcc
	v_cmp_class_f32_e32 vcc, v19, v113
	v_mul_f32_e32 v17, v17, v18
	v_mul_f32_e32 v4, v17, v4
	v_cndmask_b32_e32 v19, v21, v19, vcc
	v_mul_f32_e32 v6, v6, v19
	v_mul_f32_e32 v6, v6, v0
	v_cvt_pk_bf16_f32 v17, v1, s0
	v_lshl_add_u64 v[0:1], s[48:49], 0, v[2:3]
	global_store_short v[0:1], v17, off sc1
	global_store_short v[0:1], v5, off offset:64 sc1
	v_cvt_pk_bf16_f32 v4, v4, s0
	v_lshl_add_u64 v[0:1], s[46:47], 0, v[2:3]
	v_cvt_pk_bf16_f32 v2, v6, s0
	global_store_short v[0:1], v4, off sc1
	global_store_short v[0:1], v2, off offset:64 sc1
	v_add_u32_e32 v0, v121, v78
	v_ashrrev_i32_e32 v1, 31, v0
	v_lshlrev_b64 v[2:3], 1, v[0:1]
	v_lshl_add_u64 v[4:5], s[8:9], 0, v[2:3]
	v_mov_b32_e32 v4, v148
	v_or_b32_e32 v0, 32, v0
	v_ashrrev_i32_e32 v1, 31, v0
	v_lshl_add_u64 v[0:1], v[0:1], 1, s[8:9]
	v_mov_b32_e32 v0, v149
	v_add_f32_e32 v1, v23, v117
	v_add_f32_e32 v5, v39, v118
	v_mul_f32_e32 v1, 0xbfb8aa3b, v1
	v_mul_f32_e32 v5, 0xbfb8aa3b, v5
	v_exp_f32_e32 v1, v1
	v_exp_f32_e32 v5, v5
	v_add_f32_e32 v6, v55, v119
	v_mul_f32_e32 v6, 0xbfb8aa3b, v6
	v_add_f32_e32 v1, 1.0, v1
	v_add_f32_e32 v5, 1.0, v5
	v_rcp_f32_e32 v1, v1
	v_rcp_f32_e32 v5, v5
	v_exp_f32_e32 v6, v6
	v_mul_f32_e32 v1, v1, v120
	v_mul_f32_e32 v5, v5, v16
	v_add_f32_e32 v17, v1, v1
	v_add_f32_e32 v18, v5, v5
	v_mul_f32_e32 v17, 0x3fb8aa3b, v17
	v_mul_f32_e32 v18, 0x3fb8aa3b, v18
	v_exp_f32_e32 v17, v17
	v_exp_f32_e32 v18, v18
	v_add_f32_e32 v6, 1.0, v6
	v_rcp_f32_e32 v6, v6
	v_sub_f32_e32 v17, 1.0, v17
	v_sub_f32_e32 v18, 1.0, v18
	v_max_f32_e32 v17, 0, v17
	v_max_f32_e32 v18, 0, v18
	v_mul_f32_e32 v19, 0x4f800000, v17
	v_cmp_gt_f32_e32 vcc, s59, v17
	v_mul_f32_e32 v20, 0x4f800000, v18
	v_cmp_gt_f32_e64 s[0:1], s59, v18
	v_cndmask_b32_e32 v17, v17, v19, vcc
	v_sqrt_f32_e32 v19, v17
	v_cndmask_b32_e64 v18, v18, v20, s[0:1]
	v_sqrt_f32_e32 v20, v18
	v_cvt_pk_bf16_f32 v5, v5, s0
	v_add_u32_e32 v21, -1, v19
	v_fma_f32 v33, -v21, v19, v17
	v_add_u32_e32 v23, -1, v20
	v_add_u32_e32 v22, 1, v19
	v_fma_f32 v35, -v23, v20, v18
	v_cmp_ge_f32_e64 s[4:5], 0, v33
	v_add_u32_e32 v32, 1, v20
	v_fma_f32 v34, -v22, v19, v17
	v_cndmask_b32_e64 v19, v19, v21, s[4:5]
	v_cmp_ge_f32_e64 s[4:5], 0, v35
	v_fma_f32 v36, -v32, v20, v18
	v_lshlrev_b32_e32 v4, 16, v4
	v_cndmask_b32_e64 v20, v20, v23, s[4:5]
	v_cmp_lt_f32_e64 s[4:5], 0, v34
	v_lshlrev_b32_e32 v0, 16, v0
	v_cndmask_b32_e64 v19, v19, v22, s[4:5]
	v_mul_f32_e32 v21, 0x37800000, v19
	v_cndmask_b32_e32 v19, v19, v21, vcc
	v_cmp_class_f32_e32 vcc, v17, v113
	v_cmp_lt_f32_e64 s[4:5], 0, v36
	s_nop 0
	v_cndmask_b32_e32 v17, v19, v17, vcc
	v_mul_f32_e32 v6, v6, v17
	v_mul_f32_e32 v4, v6, v4
	v_add_f32_e32 v6, 1.0, v7
	v_cndmask_b32_e64 v20, v20, v32, s[4:5]
	v_rcp_f32_e32 v6, v6
	v_mul_f32_e32 v22, 0x37800000, v20
	v_cndmask_b32_e64 v7, v20, v22, s[0:1]
	v_cmp_class_f32_e32 vcc, v18, v113
	v_cvt_pk_bf16_f32 v4, v4, s0
	s_nop 0
	v_cndmask_b32_e32 v7, v7, v18, vcc
	v_mul_f32_e32 v6, v6, v7
	v_mul_f32_e32 v6, v6, v0
	v_cvt_pk_bf16_f32 v7, v1, s0
	v_lshl_add_u64 v[0:1], s[48:49], 0, v[2:3]
	global_store_short v[0:1], v7, off sc1
	global_store_short v[0:1], v5, off offset:64 sc1
	v_lshl_add_u64 v[0:1], s[46:47], 0, v[2:3]
	v_cvt_pk_bf16_f32 v2, v6, s0
	global_store_short v[0:1], v4, off sc1
	global_store_short v[0:1], v2, off offset:64 sc1
	v_add_u32_e32 v0, v121, v79
	v_ashrrev_i32_e32 v1, 31, v0
	v_lshlrev_b64 v[2:3], 1, v[0:1]
	v_or_b32_e32 v0, 32, v0
	v_lshl_add_u64 v[4:5], s[8:9], 0, v[2:3]
	v_ashrrev_i32_e32 v1, 31, v0
	v_lshl_add_u64 v[0:1], v[0:1], 1, s[8:9]
	v_mov_b32_e32 v4, v150
	s_nop 0
	v_mov_b32_e32 v5, v151
	v_add_f32_e32 v0, v24, v117
	v_add_f32_e32 v1, v40, v118
	v_mul_f32_e32 v0, 0xbfb8aa3b, v0
	v_add_f32_e32 v7, v8, v68
	v_mul_f32_e32 v1, 0xbfb8aa3b, v1
	v_exp_f32_e32 v8, v0
	v_exp_f32_e32 v17, v1
	v_lshl_add_u64 v[0:1], s[48:49], 0, v[2:3]
	v_add_f32_e32 v6, v56, v119
	v_add_f32_e32 v8, 1.0, v8
	v_add_f32_e32 v17, 1.0, v17
	v_rcp_f32_e32 v8, v8
	v_rcp_f32_e32 v17, v17
	v_mul_f32_e32 v6, 0xbfb8aa3b, v6
	v_mul_f32_e32 v7, 0xbfb8aa3b, v7
	v_mul_f32_e32 v8, v8, v120
	v_mul_f32_e32 v17, v17, v16
	v_add_f32_e32 v18, v8, v8
	v_add_f32_e32 v19, v17, v17
	v_mul_f32_e32 v18, 0x3fb8aa3b, v18
	v_mul_f32_e32 v19, 0x3fb8aa3b, v19
	v_exp_f32_e32 v18, v18
	v_exp_f32_e32 v19, v19
	v_cvt_pk_bf16_f32 v8, v8, s0
	global_store_short v[0:1], v8, off sc1
	v_sub_f32_e32 v8, 1.0, v18
	v_sub_f32_e32 v18, 1.0, v19
	v_max_f32_e32 v8, 0, v8
	v_max_f32_e32 v18, 0, v18
	v_mul_f32_e32 v19, 0x4f800000, v8
	v_cmp_gt_f32_e32 vcc, s59, v8
	v_cvt_pk_bf16_f32 v17, v17, s0
	v_mul_f32_e32 v20, 0x4f800000, v18
	v_cndmask_b32_e32 v8, v8, v19, vcc
	v_cmp_gt_f32_e64 s[0:1], s59, v18
	v_sqrt_f32_e32 v19, v8
	v_exp_f32_e32 v6, v6
	v_cndmask_b32_e64 v18, v18, v20, s[0:1]
	v_sqrt_f32_e32 v20, v18
	global_store_short v[0:1], v17, off offset:64 sc1
	v_add_u32_e32 v0, -1, v19
	v_exp_f32_e32 v7, v7
	v_add_u32_e32 v17, -1, v20
	v_fma_f32 v22, -v0, v19, v8
	v_add_u32_e32 v1, 1, v19
	v_fma_f32 v24, -v17, v20, v18
	v_cmp_ge_f32_e64 s[4:5], 0, v22
	v_add_u32_e32 v21, 1, v20
	v_fma_f32 v23, -v1, v19, v8
	v_cndmask_b32_e64 v0, v19, v0, s[4:5]
	v_cmp_ge_f32_e64 s[4:5], 0, v24
	v_add_f32_e32 v6, 1.0, v6
	v_fma_f32 v32, -v21, v20, v18
	v_cndmask_b32_e64 v17, v20, v17, s[4:5]
	v_cmp_lt_f32_e64 s[4:5], 0, v23
	v_add_f32_e32 v7, 1.0, v7
	v_rcp_f32_e32 v6, v6
	v_cndmask_b32_e64 v0, v0, v1, s[4:5]
	v_cmp_lt_f32_e64 s[4:5], 0, v32
	v_rcp_f32_e32 v7, v7
	v_lshl_add_u64 v[2:3], s[46:47], 0, v[2:3]
	v_cndmask_b32_e64 v1, v17, v21, s[4:5]
	v_mul_f32_e32 v17, 0x37800000, v0
	v_mul_f32_e32 v19, 0x37800000, v1
	v_cndmask_b32_e32 v0, v0, v17, vcc
	v_cmp_class_f32_e32 vcc, v8, v113
	v_cndmask_b32_e64 v1, v1, v19, s[0:1]
	v_lshlrev_b32_e32 v4, 16, v4
	v_cndmask_b32_e32 v0, v0, v8, vcc
	v_cmp_class_f32_e32 vcc, v18, v113
	v_mul_f32_e32 v0, v6, v0
	v_lshlrev_b32_e32 v5, 16, v5
	v_cndmask_b32_e32 v1, v1, v18, vcc
	v_mul_f32_e32 v1, v7, v1
	v_mul_f32_e32 v0, v0, v4
	v_mul_f32_e32 v1, v1, v5
	v_cvt_pk_bf16_f32 v0, v0, s0
	v_cvt_pk_bf16_f32 v1, v1, s0
	global_store_short v[2:3], v0, off sc1
	global_store_short v[2:3], v1, off offset:64 sc1
	v_add_u32_e32 v0, v121, v80
	v_ashrrev_i32_e32 v1, 31, v0
	v_lshlrev_b64 v[2:3], 1, v[0:1]
	v_or_b32_e32 v0, 32, v0
	v_lshl_add_u64 v[4:5], s[8:9], 0, v[2:3]
	v_ashrrev_i32_e32 v1, 31, v0
	v_lshl_add_u64 v[0:1], v[0:1], 1, s[8:9]
	v_mov_b32_e32 v4, v152
	s_nop 0
	v_mov_b32_e32 v5, v153
	v_add_f32_e32 v0, v25, v117
	v_add_f32_e32 v1, v41, v118
	v_mul_f32_e32 v0, 0xbfb8aa3b, v0
	v_mul_f32_e32 v1, 0xbfb8aa3b, v1
	v_exp_f32_e32 v8, v0
	v_add_f32_e32 v7, v9, v68
	v_exp_f32_e32 v9, v1
	v_add_f32_e32 v6, v57, v119
	v_add_f32_e32 v8, 1.0, v8
	v_rcp_f32_e32 v8, v8
	v_add_f32_e32 v9, 1.0, v9
	v_rcp_f32_e32 v9, v9
	v_mul_f32_e32 v6, 0xbfb8aa3b, v6
	v_mul_f32_e32 v8, v8, v120
	v_add_f32_e32 v17, v8, v8
	v_mul_f32_e32 v9, v9, v16
	v_add_f32_e32 v18, v9, v9
	v_mul_f32_e32 v17, 0x3fb8aa3b, v17
	v_mul_f32_e32 v18, 0x3fb8aa3b, v18
	v_exp_f32_e32 v17, v17
	v_exp_f32_e32 v18, v18
	v_mul_f32_e32 v7, 0xbfb8aa3b, v7
	v_exp_f32_e32 v6, v6
	v_sub_f32_e32 v17, 1.0, v17
	v_sub_f32_e32 v18, 1.0, v18
	v_max_f32_e32 v17, 0, v17
	v_max_f32_e32 v18, 0, v18
	v_mul_f32_e32 v19, 0x4f800000, v17
	v_cmp_gt_f32_e32 vcc, s59, v17
	v_mul_f32_e32 v20, 0x4f800000, v18
	v_cmp_gt_f32_e64 s[0:1], s59, v18
	v_cndmask_b32_e32 v17, v17, v19, vcc
	v_sqrt_f32_e32 v19, v17
	v_cndmask_b32_e64 v18, v18, v20, s[0:1]
	v_sqrt_f32_e32 v20, v18
	v_exp_f32_e32 v7, v7
	v_add_u32_e32 v21, -1, v19
	v_fma_f32 v25, -v21, v19, v17
	v_add_u32_e32 v23, -1, v20
	v_add_u32_e32 v22, 1, v19
	v_fma_f32 v33, -v23, v20, v18
	v_cmp_ge_f32_e64 s[4:5], 0, v25
	v_add_u32_e32 v24, 1, v20
	v_fma_f32 v32, -v22, v19, v17
	v_cndmask_b32_e64 v19, v19, v21, s[4:5]
	v_cmp_ge_f32_e64 s[4:5], 0, v33
	v_fma_f32 v34, -v24, v20, v18
	v_add_f32_e32 v6, 1.0, v6
	v_cndmask_b32_e64 v20, v20, v23, s[4:5]
	v_cmp_lt_f32_e64 s[4:5], 0, v32
	v_add_f32_e32 v7, 1.0, v7
	v_rcp_f32_e32 v6, v6
	v_cndmask_b32_e64 v19, v19, v22, s[4:5]
	v_cmp_lt_f32_e64 s[4:5], 0, v34
	v_rcp_f32_e32 v7, v7
	v_mul_f32_e32 v21, 0x37800000, v19
	v_cndmask_b32_e64 v20, v20, v24, s[4:5]
	v_mul_f32_e32 v22, 0x37800000, v20
	v_cndmask_b32_e32 v19, v19, v21, vcc
	v_cmp_class_f32_e32 vcc, v17, v113
	v_cndmask_b32_e64 v20, v20, v22, s[0:1]
	v_lshl_add_u64 v[0:1], s[48:49], 0, v[2:3]
	v_cndmask_b32_e32 v17, v19, v17, vcc
	v_cmp_class_f32_e32 vcc, v18, v113
	v_mul_f32_e32 v6, v6, v17
	v_cvt_pk_bf16_f32 v8, v8, s0
	v_cndmask_b32_e32 v18, v20, v18, vcc
	v_mul_f32_e32 v7, v7, v18
	global_store_short v[0:1], v8, off sc1
	v_lshlrev_b32_e32 v4, 16, v4
	v_lshlrev_b32_e32 v5, 16, v5
	v_mul_f32_e32 v4, v6, v4
	v_mul_f32_e32 v5, v7, v5
	v_cvt_pk_bf16_f32 v6, v9, s0
	global_store_short v[0:1], v6, off offset:64 sc1
	v_cvt_pk_bf16_f32 v4, v4, s0
	v_lshl_add_u64 v[0:1], s[46:47], 0, v[2:3]
	v_cvt_pk_bf16_f32 v2, v5, s0
	global_store_short v[0:1], v4, off sc1
	global_store_short v[0:1], v2, off offset:64 sc1
	v_add_u32_e32 v0, v121, v81
	v_ashrrev_i32_e32 v1, 31, v0
	v_lshlrev_b64 v[2:3], 1, v[0:1]
	v_or_b32_e32 v0, 32, v0
	v_lshl_add_u64 v[4:5], s[8:9], 0, v[2:3]
	v_ashrrev_i32_e32 v1, 31, v0
	v_mov_b32_e32 v4, v154
	v_lshl_add_u64 v[0:1], v[0:1], 1, s[8:9]
	v_mov_b32_e32 v0, v156
	v_add_f32_e32 v1, v26, v117
	v_add_f32_e32 v5, v42, v118
	v_mul_f32_e32 v1, 0xbfb8aa3b, v1
	v_mul_f32_e32 v5, 0xbfb8aa3b, v5
	v_exp_f32_e32 v1, v1
	v_exp_f32_e32 v5, v5
	v_add_f32_e32 v7, v10, v68
	v_add_f32_e32 v6, v58, v119
	v_add_f32_e32 v1, 1.0, v1
	v_add_f32_e32 v5, 1.0, v5
	v_rcp_f32_e32 v1, v1
	v_rcp_f32_e32 v5, v5
	v_mul_f32_e32 v6, 0xbfb8aa3b, v6
	v_mul_f32_e32 v7, 0xbfb8aa3b, v7
	v_mul_f32_e32 v1, v1, v120
	v_mul_f32_e32 v5, v5, v16
	v_add_f32_e32 v8, v1, v1
	v_add_f32_e32 v9, v5, v5
	v_mul_f32_e32 v8, 0x3fb8aa3b, v8
	v_mul_f32_e32 v9, 0x3fb8aa3b, v9
	v_exp_f32_e32 v8, v8
	v_exp_f32_e32 v9, v9
	v_exp_f32_e32 v6, v6
	v_exp_f32_e32 v7, v7
	v_sub_f32_e32 v8, 1.0, v8
	v_sub_f32_e32 v9, 1.0, v9
	v_max_f32_e32 v8, 0, v8
	v_max_f32_e32 v9, 0, v9
	v_mul_f32_e32 v10, 0x4f800000, v8
	v_cmp_gt_f32_e32 vcc, s59, v8
	v_mul_f32_e32 v17, 0x4f800000, v9
	v_cmp_gt_f32_e64 s[0:1], s59, v9
	v_cndmask_b32_e32 v8, v8, v10, vcc
	v_sqrt_f32_e32 v10, v8
	v_cndmask_b32_e64 v9, v9, v17, s[0:1]
	v_sqrt_f32_e32 v17, v9
	v_add_f32_e32 v6, 1.0, v6
	v_add_u32_e32 v18, -1, v10
	v_fma_f32 v22, -v18, v10, v8
	v_add_u32_e32 v20, -1, v17
	v_add_u32_e32 v19, 1, v10
	v_fma_f32 v24, -v20, v17, v9
	v_cmp_ge_f32_e64 s[4:5], 0, v22
	v_add_u32_e32 v21, 1, v17
	v_fma_f32 v23, -v19, v10, v8
	v_cndmask_b32_e64 v10, v10, v18, s[4:5]
	v_cmp_ge_f32_e64 s[4:5], 0, v24
	v_fma_f32 v25, -v21, v17, v9
	v_add_f32_e32 v7, 1.0, v7
	v_cndmask_b32_e64 v17, v17, v20, s[4:5]
	v_cmp_lt_f32_e64 s[4:5], 0, v23
	v_rcp_f32_e32 v6, v6
	v_rcp_f32_e32 v7, v7
	v_cndmask_b32_e64 v10, v10, v19, s[4:5]
	v_cmp_lt_f32_e64 s[4:5], 0, v25
	v_mul_f32_e32 v18, 0x37800000, v10
	v_cndmask_b32_e32 v10, v10, v18, vcc
	v_cndmask_b32_e64 v17, v17, v21, s[4:5]
	v_mul_f32_e32 v19, 0x37800000, v17
	v_cmp_class_f32_e32 vcc, v8, v113
	v_cndmask_b32_e64 v17, v17, v19, s[0:1]
	v_cvt_pk_bf16_f32 v5, v5, s0
	v_cndmask_b32_e32 v8, v10, v8, vcc
	v_cmp_class_f32_e32 vcc, v9, v113
	v_mul_f32_e32 v6, v6, v8
	v_lshlrev_b32_e32 v4, 16, v4
	v_cndmask_b32_e32 v9, v17, v9, vcc
	v_mul_f32_e32 v4, v6, v4
	v_mul_f32_e32 v6, v7, v9
	v_lshlrev_b32_e32 v0, 16, v0
	v_mul_f32_e32 v6, v6, v0
	v_cvt_pk_bf16_f32 v7, v1, s0
	v_lshl_add_u64 v[0:1], s[48:49], 0, v[2:3]
	global_store_short v[0:1], v7, off sc1
	global_store_short v[0:1], v5, off offset:64 sc1
	v_cvt_pk_bf16_f32 v4, v4, s0
	v_lshl_add_u64 v[0:1], s[46:47], 0, v[2:3]
	v_cvt_pk_bf16_f32 v2, v6, s0
	global_store_short v[0:1], v4, off sc1
	global_store_short v[0:1], v2, off offset:64 sc1
	v_add_u32_e32 v0, v121, v82
	v_ashrrev_i32_e32 v1, 31, v0
	v_lshlrev_b64 v[2:3], 1, v[0:1]
	v_lshl_add_u64 v[4:5], s[8:9], 0, v[2:3]
	v_mov_b32_e32 v4, v157
	v_or_b32_e32 v0, 32, v0
	v_ashrrev_i32_e32 v1, 31, v0
	v_lshl_add_u64 v[0:1], v[0:1], 1, s[8:9]
	v_mov_b32_e32 v0, v158
	v_add_f32_e32 v1, v27, v117
	v_add_f32_e32 v5, v43, v118
	v_mul_f32_e32 v1, 0xbfb8aa3b, v1
	v_mul_f32_e32 v5, 0xbfb8aa3b, v5
	v_exp_f32_e32 v1, v1
	v_exp_f32_e32 v5, v5
	v_add_f32_e32 v7, v11, v68
	v_add_f32_e32 v6, v59, v119
	v_add_f32_e32 v1, 1.0, v1
	v_add_f32_e32 v5, 1.0, v5
	v_rcp_f32_e32 v1, v1
	v_rcp_f32_e32 v5, v5
	v_mul_f32_e32 v6, 0xbfb8aa3b, v6
	v_exp_f32_e32 v6, v6
	v_mul_f32_e32 v1, v1, v120
	v_mul_f32_e32 v5, v5, v16
	v_add_f32_e32 v8, v1, v1
	v_add_f32_e32 v9, v5, v5
	v_mul_f32_e32 v8, 0x3fb8aa3b, v8
	v_mul_f32_e32 v9, 0x3fb8aa3b, v9
	v_exp_f32_e32 v8, v8
	v_exp_f32_e32 v9, v9
	v_add_f32_e32 v6, 1.0, v6
	v_mul_f32_e32 v7, 0xbfb8aa3b, v7
	v_sub_f32_e32 v8, 1.0, v8
	v_sub_f32_e32 v9, 1.0, v9
	v_max_f32_e32 v8, 0, v8
	v_max_f32_e32 v9, 0, v9
	v_mul_f32_e32 v10, 0x4f800000, v8
	v_cmp_gt_f32_e32 vcc, s59, v8
	v_mul_f32_e32 v11, 0x4f800000, v9
	v_cmp_gt_f32_e64 s[0:1], s59, v9
	v_cndmask_b32_e32 v8, v8, v10, vcc
	v_sqrt_f32_e32 v10, v8
	v_cndmask_b32_e64 v9, v9, v11, s[0:1]
	v_sqrt_f32_e32 v11, v9
	v_rcp_f32_e32 v6, v6
	v_add_u32_e32 v17, -1, v10
	v_fma_f32 v21, -v17, v10, v8
	v_add_u32_e32 v19, -1, v11
	v_add_u32_e32 v18, 1, v10
	v_fma_f32 v23, -v19, v11, v9
	v_cmp_ge_f32_e64 s[4:5], 0, v21
	v_add_u32_e32 v20, 1, v11
	v_fma_f32 v22, -v18, v10, v8
	v_cndmask_b32_e64 v10, v10, v17, s[4:5]
	v_cmp_ge_f32_e64 s[4:5], 0, v23
	v_fma_f32 v24, -v20, v11, v9
	v_exp_f32_e32 v7, v7
	v_cndmask_b32_e64 v11, v11, v19, s[4:5]
	v_cmp_lt_f32_e64 s[4:5], 0, v22
	v_cvt_pk_bf16_f32 v5, v5, s0
	v_lshlrev_b32_e32 v4, 16, v4
	v_cndmask_b32_e64 v10, v10, v18, s[4:5]
	v_mul_f32_e32 v17, 0x37800000, v10
	v_cndmask_b32_e32 v10, v10, v17, vcc
	v_cmp_class_f32_e32 vcc, v8, v113
	v_cmp_lt_f32_e64 s[4:5], 0, v24
	v_lshlrev_b32_e32 v0, 16, v0
	v_cndmask_b32_e32 v8, v10, v8, vcc
	v_mul_f32_e32 v6, v6, v8
	v_mul_f32_e32 v4, v6, v4
	v_add_f32_e32 v6, 1.0, v7
	v_cndmask_b32_e64 v11, v11, v20, s[4:5]
	v_rcp_f32_e32 v6, v6
	v_mul_f32_e32 v18, 0x37800000, v11
	v_cndmask_b32_e64 v7, v11, v18, s[0:1]
	v_cmp_class_f32_e32 vcc, v9, v113
	v_cvt_pk_bf16_f32 v4, v4, s0
	s_nop 0
	v_cndmask_b32_e32 v7, v7, v9, vcc
	v_mul_f32_e32 v6, v6, v7
	v_mul_f32_e32 v6, v6, v0
	v_cvt_pk_bf16_f32 v7, v1, s0
	v_lshl_add_u64 v[0:1], s[48:49], 0, v[2:3]
	global_store_short v[0:1], v7, off sc1
	global_store_short v[0:1], v5, off offset:64 sc1
	v_lshl_add_u64 v[0:1], s[46:47], 0, v[2:3]
	v_cvt_pk_bf16_f32 v2, v6, s0
	global_store_short v[0:1], v4, off sc1
	global_store_short v[0:1], v2, off offset:64 sc1
	v_add_u32_e32 v0, v121, v83
	v_ashrrev_i32_e32 v1, 31, v0
	v_lshlrev_b64 v[2:3], 1, v[0:1]
	v_or_b32_e32 v0, 32, v0
	v_lshl_add_u64 v[4:5], s[8:9], 0, v[2:3]
	v_ashrrev_i32_e32 v1, 31, v0
	v_lshl_add_u64 v[0:1], v[0:1], 1, s[8:9]
	v_mov_b32_e32 v4, v159
	s_nop 0
	v_mov_b32_e32 v5, v160
	v_add_f32_e32 v0, v28, v117
	v_add_f32_e32 v1, v44, v118
	v_mul_f32_e32 v0, 0xbfb8aa3b, v0
	v_mul_f32_e32 v1, 0xbfb8aa3b, v1
	v_exp_f32_e32 v8, v0
	v_exp_f32_e32 v9, v1
	v_lshl_add_u64 v[0:1], s[48:49], 0, v[2:3]
	v_add_f32_e32 v7, v12, v68
	v_add_f32_e32 v8, 1.0, v8
	v_add_f32_e32 v9, 1.0, v9
	v_rcp_f32_e32 v8, v8
	v_rcp_f32_e32 v9, v9
	v_add_f32_e32 v6, v60, v119
	v_mul_f32_e32 v6, 0xbfb8aa3b, v6
	v_mul_f32_e32 v8, v8, v120
	v_mul_f32_e32 v9, v9, v16
	v_add_f32_e32 v10, v8, v8
	v_add_f32_e32 v11, v9, v9
	v_mul_f32_e32 v10, 0x3fb8aa3b, v10
	v_mul_f32_e32 v11, 0x3fb8aa3b, v11
	v_exp_f32_e32 v10, v10
	v_exp_f32_e32 v11, v11
	v_cvt_pk_bf16_f32 v8, v8, s0
	global_store_short v[0:1], v8, off sc1
	v_sub_f32_e32 v8, 1.0, v10
	v_sub_f32_e32 v10, 1.0, v11
	v_max_f32_e32 v8, 0, v8
	v_max_f32_e32 v10, 0, v10
	v_mul_f32_e32 v11, 0x4f800000, v8
	v_cmp_gt_f32_e32 vcc, s59, v8
	v_cvt_pk_bf16_f32 v9, v9, s0
	v_mul_f32_e32 v12, 0x4f800000, v10
	v_cndmask_b32_e32 v8, v8, v11, vcc
	v_cmp_gt_f32_e64 s[0:1], s59, v10
	v_sqrt_f32_e32 v11, v8
	v_mul_f32_e32 v7, 0xbfb8aa3b, v7
	v_cndmask_b32_e64 v10, v10, v12, s[0:1]
	v_sqrt_f32_e32 v12, v10
	v_exp_f32_e32 v6, v6
	global_store_short v[0:1], v9, off offset:64 sc1
	v_add_u32_e32 v0, -1, v11
	v_exp_f32_e32 v7, v7
	v_add_u32_e32 v9, -1, v12
	v_fma_f32 v18, -v0, v11, v8
	v_add_u32_e32 v1, 1, v11
	v_fma_f32 v20, -v9, v12, v10
	v_cmp_ge_f32_e64 s[4:5], 0, v18
	v_add_u32_e32 v17, 1, v12
	v_fma_f32 v19, -v1, v11, v8
	v_cndmask_b32_e64 v0, v11, v0, s[4:5]
	v_cmp_ge_f32_e64 s[4:5], 0, v20
	v_add_f32_e32 v6, 1.0, v6
	v_fma_f32 v21, -v17, v12, v10
	v_cndmask_b32_e64 v9, v12, v9, s[4:5]
	v_cmp_lt_f32_e64 s[4:5], 0, v19
	v_add_f32_e32 v7, 1.0, v7
	v_rcp_f32_e32 v6, v6
	v_cndmask_b32_e64 v0, v0, v1, s[4:5]
	v_cmp_lt_f32_e64 s[4:5], 0, v21
	v_rcp_f32_e32 v7, v7
	v_lshl_add_u64 v[2:3], s[46:47], 0, v[2:3]
	v_cndmask_b32_e64 v1, v9, v17, s[4:5]
	v_mul_f32_e32 v9, 0x37800000, v0
	v_mul_f32_e32 v11, 0x37800000, v1
	v_cndmask_b32_e32 v0, v0, v9, vcc
	v_cmp_class_f32_e32 vcc, v8, v113
	v_cndmask_b32_e64 v1, v1, v11, s[0:1]
	v_lshlrev_b32_e32 v4, 16, v4
	v_cndmask_b32_e32 v0, v0, v8, vcc
	v_cmp_class_f32_e32 vcc, v10, v113
	v_mul_f32_e32 v0, v6, v0
	v_lshlrev_b32_e32 v5, 16, v5
	v_cndmask_b32_e32 v1, v1, v10, vcc
	v_mul_f32_e32 v1, v7, v1
	v_mul_f32_e32 v0, v0, v4
	v_mul_f32_e32 v1, v1, v5
	v_cvt_pk_bf16_f32 v0, v0, s0
	v_cvt_pk_bf16_f32 v1, v1, s0
	global_store_short v[2:3], v0, off sc1
	global_store_short v[2:3], v1, off offset:64 sc1
	v_add_u32_e32 v0, v121, v84
	v_ashrrev_i32_e32 v1, 31, v0
	v_lshlrev_b64 v[2:3], 1, v[0:1]
	v_or_b32_e32 v0, 32, v0
	v_lshl_add_u64 v[4:5], s[8:9], 0, v[2:3]
	v_ashrrev_i32_e32 v1, 31, v0
	v_lshl_add_u64 v[0:1], v[0:1], 1, s[8:9]
	v_mov_b32_e32 v4, v161
	s_nop 0
	v_mov_b32_e32 v5, v162
	v_add_f32_e32 v0, v29, v117
	v_add_f32_e32 v1, v45, v118
	v_mul_f32_e32 v0, 0xbfb8aa3b, v0
	v_mul_f32_e32 v1, 0xbfb8aa3b, v1
	v_exp_f32_e32 v8, v0
	v_exp_f32_e32 v9, v1
	v_add_f32_e32 v7, v13, v68
	v_add_f32_e32 v6, v61, v119
	v_add_f32_e32 v8, 1.0, v8
	v_add_f32_e32 v9, 1.0, v9
	v_rcp_f32_e32 v8, v8
	v_rcp_f32_e32 v9, v9
	v_mul_f32_e32 v6, 0xbfb8aa3b, v6
	v_mul_f32_e32 v7, 0xbfb8aa3b, v7
	v_mul_f32_e32 v8, v8, v120
	v_mul_f32_e32 v9, v9, v16
	v_add_f32_e32 v10, v8, v8
	v_add_f32_e32 v11, v9, v9
	v_mul_f32_e32 v10, 0x3fb8aa3b, v10
	v_mul_f32_e32 v11, 0x3fb8aa3b, v11
	v_exp_f32_e32 v10, v10
	v_exp_f32_e32 v11, v11
	v_exp_f32_e32 v6, v6
	v_exp_f32_e32 v7, v7
	v_sub_f32_e32 v10, 1.0, v10
	v_sub_f32_e32 v11, 1.0, v11
	v_max_f32_e32 v10, 0, v10
	v_max_f32_e32 v11, 0, v11
	v_mul_f32_e32 v12, 0x4f800000, v10
	v_cmp_gt_f32_e32 vcc, s59, v10
	v_mul_f32_e32 v13, 0x4f800000, v11
	v_cmp_gt_f32_e64 s[0:1], s59, v11
	v_cndmask_b32_e32 v10, v10, v12, vcc
	v_sqrt_f32_e32 v12, v10
	v_cndmask_b32_e64 v11, v11, v13, s[0:1]
	v_sqrt_f32_e32 v13, v11
	v_add_f32_e32 v6, 1.0, v6
	v_add_u32_e32 v17, -1, v12
	v_fma_f32 v21, -v17, v12, v10
	v_add_u32_e32 v19, -1, v13
	v_add_u32_e32 v18, 1, v12
	v_fma_f32 v23, -v19, v13, v11
	v_cmp_ge_f32_e64 s[4:5], 0, v21
	v_add_u32_e32 v20, 1, v13
	v_fma_f32 v22, -v18, v12, v10
	v_cndmask_b32_e64 v12, v12, v17, s[4:5]
	v_cmp_ge_f32_e64 s[4:5], 0, v23
	v_fma_f32 v24, -v20, v13, v11
	v_add_f32_e32 v7, 1.0, v7
	v_cndmask_b32_e64 v13, v13, v19, s[4:5]
	v_cmp_lt_f32_e64 s[4:5], 0, v22
	v_rcp_f32_e32 v6, v6
	v_rcp_f32_e32 v7, v7
	v_cndmask_b32_e64 v12, v12, v18, s[4:5]
	v_cmp_lt_f32_e64 s[4:5], 0, v24
	v_mul_f32_e32 v17, 0x37800000, v12
	v_cndmask_b32_e32 v12, v12, v17, vcc
	v_cndmask_b32_e64 v13, v13, v20, s[4:5]
	v_mul_f32_e32 v18, 0x37800000, v13
	v_cmp_class_f32_e32 vcc, v10, v113
	v_cndmask_b32_e64 v13, v13, v18, s[0:1]
	v_lshl_add_u64 v[0:1], s[48:49], 0, v[2:3]
	v_cndmask_b32_e32 v10, v12, v10, vcc
	v_cmp_class_f32_e32 vcc, v11, v113
	v_mul_f32_e32 v6, v6, v10
	v_cvt_pk_bf16_f32 v8, v8, s0
	v_cndmask_b32_e32 v11, v13, v11, vcc
	v_mul_f32_e32 v7, v7, v11
	global_store_short v[0:1], v8, off sc1
	v_lshlrev_b32_e32 v4, 16, v4
	v_lshlrev_b32_e32 v5, 16, v5
	v_mul_f32_e32 v4, v6, v4
	v_mul_f32_e32 v5, v7, v5
	v_cvt_pk_bf16_f32 v6, v9, s0
	global_store_short v[0:1], v6, off offset:64 sc1
	v_cvt_pk_bf16_f32 v4, v4, s0
	v_lshl_add_u64 v[0:1], s[46:47], 0, v[2:3]
	v_cvt_pk_bf16_f32 v2, v5, s0
	global_store_short v[0:1], v4, off sc1
	global_store_short v[0:1], v2, off offset:64 sc1
	v_add_u32_e32 v0, v121, v85
	v_ashrrev_i32_e32 v1, 31, v0
	v_lshlrev_b64 v[2:3], 1, v[0:1]
	v_or_b32_e32 v0, 32, v0
	v_lshl_add_u64 v[4:5], s[8:9], 0, v[2:3]
	v_ashrrev_i32_e32 v1, 31, v0
	v_mov_b32_e32 v4, v163
	v_lshl_add_u64 v[0:1], v[0:1], 1, s[8:9]
	v_mov_b32_e32 v0, v164
	v_add_f32_e32 v1, v30, v117
	v_add_f32_e32 v5, v46, v118
	v_mul_f32_e32 v1, 0xbfb8aa3b, v1
	v_mul_f32_e32 v5, 0xbfb8aa3b, v5
	v_exp_f32_e32 v1, v1
	v_exp_f32_e32 v5, v5
	v_add_f32_e32 v6, v62, v119
	v_add_f32_e32 v7, v14, v68
	v_add_f32_e32 v1, 1.0, v1
	v_add_f32_e32 v5, 1.0, v5
	v_rcp_f32_e32 v1, v1
	v_rcp_f32_e32 v5, v5
	v_mul_f32_e32 v6, 0xbfb8aa3b, v6
	v_mul_f32_e32 v7, 0xbfb8aa3b, v7
	v_mul_f32_e32 v1, v1, v120
	v_mul_f32_e32 v5, v5, v16
	v_add_f32_e32 v8, v1, v1
	v_add_f32_e32 v9, v5, v5
	v_mul_f32_e32 v8, 0x3fb8aa3b, v8
	v_mul_f32_e32 v9, 0x3fb8aa3b, v9
	v_exp_f32_e32 v8, v8
	v_exp_f32_e32 v9, v9
	v_exp_f32_e32 v6, v6
	v_exp_f32_e32 v7, v7
	v_sub_f32_e32 v8, 1.0, v8
	v_sub_f32_e32 v9, 1.0, v9
	v_max_f32_e32 v8, 0, v8
	v_max_f32_e32 v9, 0, v9
	v_mul_f32_e32 v10, 0x4f800000, v8
	v_cmp_gt_f32_e32 vcc, s59, v8
	v_mul_f32_e32 v11, 0x4f800000, v9
	v_cmp_gt_f32_e64 s[0:1], s59, v9
	v_cndmask_b32_e32 v8, v8, v10, vcc
	v_sqrt_f32_e32 v10, v8
	v_cndmask_b32_e64 v9, v9, v11, s[0:1]
	v_sqrt_f32_e32 v11, v9
	v_add_f32_e32 v6, 1.0, v6
	v_add_u32_e32 v12, -1, v10
	v_fma_f32 v18, -v12, v10, v8
	v_add_u32_e32 v14, -1, v11
	v_add_u32_e32 v13, 1, v10
	v_fma_f32 v20, -v14, v11, v9
	v_cmp_ge_f32_e64 s[4:5], 0, v18
	v_add_u32_e32 v17, 1, v11
	v_fma_f32 v19, -v13, v10, v8
	v_cndmask_b32_e64 v10, v10, v12, s[4:5]
	v_cmp_ge_f32_e64 s[4:5], 0, v20
	v_fma_f32 v21, -v17, v11, v9
	v_add_f32_e32 v7, 1.0, v7
	v_cndmask_b32_e64 v11, v11, v14, s[4:5]
	v_cmp_lt_f32_e64 s[4:5], 0, v19
	v_rcp_f32_e32 v6, v6
	v_rcp_f32_e32 v7, v7
	v_cndmask_b32_e64 v10, v10, v13, s[4:5]
	v_cmp_lt_f32_e64 s[4:5], 0, v21
	v_mul_f32_e32 v12, 0x37800000, v10
	v_cndmask_b32_e32 v10, v10, v12, vcc
	v_cndmask_b32_e64 v11, v11, v17, s[4:5]
	v_mul_f32_e32 v13, 0x37800000, v11
	v_cmp_class_f32_e32 vcc, v8, v113
	v_cndmask_b32_e64 v11, v11, v13, s[0:1]
	v_cvt_pk_bf16_f32 v5, v5, s0
	v_cndmask_b32_e32 v8, v10, v8, vcc
	v_cmp_class_f32_e32 vcc, v9, v113
	v_mul_f32_e32 v6, v6, v8
	v_lshlrev_b32_e32 v4, 16, v4
	v_cndmask_b32_e32 v9, v11, v9, vcc
	v_mul_f32_e32 v4, v6, v4
	v_mul_f32_e32 v6, v7, v9
	v_lshlrev_b32_e32 v0, 16, v0
	v_mul_f32_e32 v6, v6, v0
	v_cvt_pk_bf16_f32 v7, v1, s0
	v_lshl_add_u64 v[0:1], s[48:49], 0, v[2:3]
	global_store_short v[0:1], v7, off sc1
	global_store_short v[0:1], v5, off offset:64 sc1
	v_cvt_pk_bf16_f32 v4, v4, s0
	v_lshl_add_u64 v[0:1], s[46:47], 0, v[2:3]
	v_cvt_pk_bf16_f32 v2, v6, s0
	global_store_short v[0:1], v4, off sc1
	global_store_short v[0:1], v2, off offset:64 sc1
	v_add_u32_e32 v0, v121, v86
	v_ashrrev_i32_e32 v1, 31, v0
	v_lshlrev_b64 v[2:3], 1, v[0:1]
	v_lshl_add_u64 v[4:5], s[8:9], 0, v[2:3]
	v_mov_b32_e32 v4, v165
	v_or_b32_e32 v0, 32, v0
	v_ashrrev_i32_e32 v1, 31, v0
	v_lshl_add_u64 v[0:1], v[0:1], 1, s[8:9]
	v_mov_b32_e32 v0, v166
	v_add_f32_e32 v1, v31, v117
	v_add_f32_e32 v5, v47, v118
	v_mul_f32_e32 v1, 0xbfb8aa3b, v1
	v_mul_f32_e32 v5, 0xbfb8aa3b, v5
	v_exp_f32_e32 v1, v1
	v_exp_f32_e32 v5, v5
	v_add_f32_e32 v6, v63, v119
	v_mul_f32_e32 v6, 0xbfb8aa3b, v6
	v_add_f32_e32 v1, 1.0, v1
	v_add_f32_e32 v5, 1.0, v5
	v_rcp_f32_e32 v1, v1
	v_rcp_f32_e32 v5, v5
	v_exp_f32_e32 v6, v6
	v_add_f32_e32 v7, v15, v68
	v_mul_f32_e32 v1, v1, v120
	v_mul_f32_e32 v5, v5, v16
	v_add_f32_e32 v8, v1, v1
	v_add_f32_e32 v9, v5, v5
	v_mul_f32_e32 v8, 0x3fb8aa3b, v8
	v_mul_f32_e32 v9, 0x3fb8aa3b, v9
	v_exp_f32_e32 v8, v8
	v_exp_f32_e32 v9, v9
	v_add_f32_e32 v6, 1.0, v6
	v_mul_f32_e32 v7, 0xbfb8aa3b, v7
	v_sub_f32_e32 v8, 1.0, v8
	v_sub_f32_e32 v9, 1.0, v9
	v_max_f32_e32 v8, 0, v8
	v_max_f32_e32 v9, 0, v9
	v_mul_f32_e32 v10, 0x4f800000, v8
	v_cmp_gt_f32_e32 vcc, s59, v8
	v_mul_f32_e32 v11, 0x4f800000, v9
	v_cmp_gt_f32_e64 s[0:1], s59, v9
	v_cndmask_b32_e32 v8, v8, v10, vcc
	v_sqrt_f32_e32 v10, v8
	v_cndmask_b32_e64 v9, v9, v11, s[0:1]
	v_sqrt_f32_e32 v11, v9
	v_rcp_f32_e32 v6, v6
	v_add_u32_e32 v12, -1, v10
	v_fma_f32 v16, -v12, v10, v8
	v_add_u32_e32 v14, -1, v11
	v_add_u32_e32 v13, 1, v10
	v_fma_f32 v18, -v14, v11, v9
	v_cmp_ge_f32_e64 s[4:5], 0, v16
	v_add_u32_e32 v15, 1, v11
	v_fma_f32 v17, -v13, v10, v8
	v_cndmask_b32_e64 v10, v10, v12, s[4:5]
	v_cmp_ge_f32_e64 s[4:5], 0, v18
	v_fma_f32 v19, -v15, v11, v9
	v_exp_f32_e32 v7, v7
	v_cndmask_b32_e64 v11, v11, v14, s[4:5]
	v_cmp_lt_f32_e64 s[4:5], 0, v17
	v_cvt_pk_bf16_f32 v5, v5, s0
	v_lshlrev_b32_e32 v4, 16, v4
	v_cndmask_b32_e64 v10, v10, v13, s[4:5]
	v_mul_f32_e32 v12, 0x37800000, v10
	v_cndmask_b32_e32 v10, v10, v12, vcc
	v_cmp_class_f32_e32 vcc, v8, v113
	v_cmp_lt_f32_e64 s[4:5], 0, v19
	v_lshlrev_b32_e32 v0, 16, v0
	v_cndmask_b32_e32 v8, v10, v8, vcc
	v_mul_f32_e32 v6, v6, v8
	v_mul_f32_e32 v4, v6, v4
	v_add_f32_e32 v6, 1.0, v7
	v_cndmask_b32_e64 v11, v11, v15, s[4:5]
	v_rcp_f32_e32 v6, v6
	v_mul_f32_e32 v13, 0x37800000, v11
	v_cndmask_b32_e64 v7, v11, v13, s[0:1]
	v_cmp_class_f32_e32 vcc, v9, v113
	v_cvt_pk_bf16_f32 v4, v4, s0
	s_nop 0
	v_cndmask_b32_e32 v7, v7, v9, vcc
	v_mul_f32_e32 v6, v6, v7
	v_mul_f32_e32 v6, v6, v0
	v_cvt_pk_bf16_f32 v7, v1, s0
	v_lshl_add_u64 v[0:1], s[48:49], 0, v[2:3]
	global_store_short v[0:1], v7, off sc1
	global_store_short v[0:1], v5, off offset:64 sc1
	v_lshl_add_u64 v[0:1], s[46:47], 0, v[2:3]
	v_cvt_pk_bf16_f32 v2, v6, s0
	global_store_short v[0:1], v4, off sc1
	global_store_short v[0:1], v2, off offset:64 sc1
	s_add_i32 s3, s3, s33
	s_cmpk_lt_i32 s3, 0x1000
	s_cbranch_scc1 .LBB0_1494
